# attention output reduction across lane groups via permlane32/16 swap + DPP instead of 192 ds_bpermute; stores from 32 lanes
# speedup vs baseline: 1.0413x; 1.0109x over previous
; __device__ __forceinline__ void dsa_attend(const h16* PROJ, const unsigned short* IDX, const int* CNT, h16* MIXA, unsigned char* shm, unsigned* bar, unsigned xcc, unsigned xrank) {
;     ...
;             for (int s0 = 0; s0 < nsel; s0 += 128) {
;                 uint4 vv[16];
; #pragma unroll
;                 for (int e = 0; e < 16; ++e) { const int slot = s0 + 8 * e + r8; const int idx = (int)sel[qq * 256 + (slot < nsel ? slot : nsel - 1)];
;                     vv[e] = *(const uint4*)(vbase8 + (size_t)idx * 128); }
;                 __builtin_amdgcn_sched_barrier(0);
; #pragma unroll
;                 for (int e = 0; e < 16; ++e) { const int slot = s0 + 8 * e + r8;
;                     if ((e & 3) == 0) __builtin_amdgcn_sched_barrier(0);
;                     const f32x4 pp = *(const f32x4*)(Pl + ((size_t)wid * 256 + slot) * 4);
.LBB0_849:
	v_add_u32_e32 v4, s50, v193
	v_add_u32_e32 v5, 32, v4
	v_add_u32_e32 v6, 40, v4
	v_add_u32_e32 v7, 48, v4
	v_add_u32_e32 v8, 56, v4
	v_min_u32_e32 v0, s70, v4
	v_add_u32_e32 v1, 8, v4
	v_add_u32_e32 v2, 16, v4
	v_add_u32_e32 v3, 24, v4
	v_min_u32_e32 v5, s70, v5
	v_min_u32_e32 v6, s70, v6
	v_min_u32_e32 v7, s70, v7
	v_min_u32_e32 v8, s70, v8
	v_lshl_add_u32 v0, v0, 1, v190
	v_min_u32_e32 v1, s70, v1
	v_min_u32_e32 v2, s70, v2
	v_min_u32_e32 v3, s70, v3
	v_lshl_add_u32 v5, v5, 1, v190
	v_lshl_add_u32 v6, v6, 1, v190
	v_lshl_add_u32 v7, v7, 1, v190
	v_lshl_add_u32 v8, v8, 1, v190
	v_lshl_add_u32 v1, v1, 1, v190
	v_lshl_add_u32 v2, v2, 1, v190
	v_lshl_add_u32 v3, v3, 1, v190
	ds_read_u16 v0, v0 offset:32768
	ds_read_u16 v9, v1 offset:32768
	ds_read_u16 v10, v2 offset:32768
	ds_read_u16 v11, v3 offset:32768
	ds_read_u16 v5, v5 offset:32768
	ds_read_u16 v6, v6 offset:32768
	ds_read_u16 v7, v7 offset:32768
	ds_read_u16 v8, v8 offset:32768
	s_waitcnt lgkmcnt(7)
	v_lshlrev_b32_e32 v162, 7, v0
	v_lshl_add_u64 v[0:1], v[142:143], 0, v[162:163]
	s_waitcnt lgkmcnt(6)
	v_lshlrev_b32_e32 v162, 7, v9
	v_lshl_add_u64 v[2:3], v[142:143], 0, v[162:163]
	s_waitcnt lgkmcnt(5)
	v_lshlrev_b32_e32 v162, 7, v10
	global_load_dwordx4 v[226:229], v[0:1], off
	global_load_dwordx4 v[56:59], v[2:3], off
	v_lshl_add_u64 v[0:1], v[142:143], 0, v[162:163]
	s_waitcnt lgkmcnt(4)
	v_lshlrev_b32_e32 v162, 7, v11
	v_lshl_add_u64 v[2:3], v[142:143], 0, v[162:163]
	s_waitcnt lgkmcnt(3)
	v_lshlrev_b32_e32 v162, 7, v5
	global_load_dwordx4 v[52:55], v[0:1], off
	global_load_dwordx4 v[48:51], v[2:3], off
	v_lshl_add_u64 v[0:1], v[142:143], 0, v[162:163]
	s_waitcnt lgkmcnt(2)
	v_lshlrev_b32_e32 v162, 7, v6
	v_lshl_add_u64 v[2:3], v[142:143], 0, v[162:163]
	s_waitcnt lgkmcnt(1)
	v_lshlrev_b32_e32 v162, 7, v7
	global_load_dwordx4 v[44:47], v[0:1], off
	global_load_dwordx4 v[40:43], v[2:3], off
	v_lshl_add_u64 v[0:1], v[142:143], 0, v[162:163]
	s_waitcnt lgkmcnt(0)
	v_lshlrev_b32_e32 v162, 7, v8
	v_lshl_add_u64 v[2:3], v[142:143], 0, v[162:163]
	global_load_dwordx4 v[36:39], v[0:1], off
	global_load_dwordx4 v[28:31], v[2:3], off
	v_add_u32_e32 v0, 64, v4
	v_add_u32_e32 v1, 0x48, v4
	v_add_u32_e32 v2, 0x50, v4
	v_add_u32_e32 v3, 0x58, v4
	v_add_u32_e32 v5, 0x60, v4
	v_add_u32_e32 v6, 0x68, v4
	v_add_u32_e32 v7, 0x70, v4
	v_add_u32_e32 v4, 0x78, v4
	v_min_u32_e32 v0, s70, v0
	v_min_u32_e32 v5, s70, v5
	v_min_u32_e32 v6, s70, v6
	v_min_u32_e32 v7, s70, v7
	v_min_u32_e32 v4, s70, v4
	v_lshl_add_u32 v0, v0, 1, v190
	v_min_u32_e32 v1, s70, v1
	v_min_u32_e32 v2, s70, v2
	v_min_u32_e32 v3, s70, v3
	v_lshl_add_u32 v5, v5, 1, v190
	v_lshl_add_u32 v6, v6, 1, v190
	v_lshl_add_u32 v7, v7, 1, v190
	v_lshl_add_u32 v4, v4, 1, v190
	v_lshl_add_u32 v1, v1, 1, v190
	v_lshl_add_u32 v2, v2, 1, v190
	v_lshl_add_u32 v3, v3, 1, v190
	ds_read_u16 v0, v0 offset:32768
	ds_read_u16 v8, v1 offset:32768
	ds_read_u16 v9, v2 offset:32768
	ds_read_u16 v10, v3 offset:32768
	ds_read_u16 v5, v5 offset:32768
	ds_read_u16 v6, v6 offset:32768
	ds_read_u16 v7, v7 offset:32768
	ds_read_u16 v4, v4 offset:32768
	s_waitcnt lgkmcnt(7)
	v_lshlrev_b32_e32 v162, 7, v0
	v_lshl_add_u64 v[0:1], v[142:143], 0, v[162:163]
	s_waitcnt lgkmcnt(6)
	v_lshlrev_b32_e32 v162, 7, v8
	v_lshl_add_u64 v[2:3], v[142:143], 0, v[162:163]
	s_waitcnt lgkmcnt(5)
	v_lshlrev_b32_e32 v162, 7, v9
	global_load_dwordx4 v[32:35], v[0:1], off
	global_load_dwordx4 v[24:27], v[2:3], off
	v_lshl_add_u64 v[0:1], v[142:143], 0, v[162:163]
	s_waitcnt lgkmcnt(4)
	v_lshlrev_b32_e32 v162, 7, v10
	v_lshl_add_u64 v[2:3], v[142:143], 0, v[162:163]
	s_waitcnt lgkmcnt(3)
	v_lshlrev_b32_e32 v162, 7, v5
	global_load_dwordx4 v[20:23], v[0:1], off
	global_load_dwordx4 v[16:19], v[2:3], off
	v_lshl_add_u64 v[0:1], v[142:143], 0, v[162:163]
	s_waitcnt lgkmcnt(2)
	v_lshlrev_b32_e32 v162, 7, v6
	v_lshl_add_u64 v[2:3], v[142:143], 0, v[162:163]
	s_waitcnt lgkmcnt(1)
	v_lshlrev_b32_e32 v162, 7, v7
	global_load_dwordx4 v[12:15], v[0:1], off
	global_load_dwordx4 v[8:11], v[2:3], off
	v_lshl_add_u64 v[0:1], v[142:143], 0, v[162:163]
	s_waitcnt lgkmcnt(0)
	v_lshlrev_b32_e32 v162, 7, v4
	v_lshl_add_u64 v[2:3], v[142:143], 0, v[162:163]
	global_load_dwordx4 v[4:7], v[0:1], off
	s_nop 0
	global_load_dwordx4 v[0:3], v[2:3], off
	ds_read_b128 v[230:233], v225
	s_waitcnt vmcnt(15)
	v_cvt_pk_f32_fp8_e32 v[124:125], v226
	v_cvt_pk_f32_fp8_sdwa v[126:127], v226 src0_sel:WORD_1
	s_waitcnt lgkmcnt(0)
; __device__ __forceinline__ void dsa_attend(const h16* PROJ, const unsigned short* IDX, const int* CNT, h16* MIXA, unsigned char* shm, unsigned* bar, unsigned xcc, unsigned xrank) {
;     ...
;                 for (int e = 0; e < 16; ++e) { const int slot = s0 + 8 * e + r8;
;                     if ((e & 3) == 0) __builtin_amdgcn_sched_barrier(0);
;                     const f32x4 pp = *(const f32x4*)(Pl + ((size_t)wid * 256 + slot) * 4);
;                     const f32x2 p0 = (f32x2){pp.x, pp.x}, p1 = (f32x2){pp.y, pp.y}, p2 = (f32x2){pp.z, pp.z}, p3 = (f32x2){pp.w, pp.w};
;                     const unsigned wds[4] = {vv[e].x, vv[e].y, vv[e].z, vv[e].w};
; #pragma unroll
;                     for (int w = 0; w < 4; ++w) {
;                         const f32x2 lo = __builtin_amdgcn_cvt_pk_f32_fp8((int)wds[w], false), hi = __builtin_amdgcn_cvt_pk_f32_fp8((int)wds[w], true);
;                         oa2[0][2 * w] = __builtin_elementwise_fma(lo, p0, oa2[0][2 * w]); oa2[0][2 * w + 1] = __builtin_elementwise_fma(hi, p0, oa2[0][2 * w + 1]);
;                         oa2[1][2 * w] = __builtin_elementwise_fma(lo, p1, oa2[1][2 * w]); oa2[1][2 * w + 1] = __builtin_elementwise_fma(hi, p1, oa2[1][2 * w + 1]);
;                         oa2[2][2 * w] = __builtin_elementwise_fma(lo, p2, oa2[2][2 * w]); oa2[2][2 * w + 1] = __builtin_elementwise_fma(hi, p2, oa2[2][2 * w + 1]);
;                         oa2[3][2 * w] = __builtin_elementwise_fma(lo, p3, oa2[3][2 * w]); oa2[3][2 * w + 1] = __builtin_elementwise_fma(hi, p3, oa2[3][2 * w + 1]); }
	v_mov_b32_e32 v162, v233
	v_pk_fma_f32 v[184:185], v[124:125], v[162:163], v[68:69] op_sel_hi:[1,0,1]
	v_pk_fma_f32 v[186:187], v[126:127], v[162:163], v[60:61] op_sel_hi:[1,0,1]
	v_cvt_pk_f32_fp8_e32 v[60:61], v227
	v_cvt_pk_f32_fp8_sdwa v[68:69], v227 src0_sel:WORD_1
	v_pk_fma_f32 v[148:149], v[124:125], v[230:231], v[110:111] op_sel_hi:[1,0,1]
	v_pk_fma_f32 v[150:151], v[126:127], v[230:231], v[112:113] op_sel_hi:[1,0,1]
	v_pk_fma_f32 v[152:153], v[124:125], v[230:231], v[104:105] op_sel:[0,1,0]
	v_pk_fma_f32 v[154:155], v[126:127], v[230:231], v[92:93] op_sel:[0,1,0]
	v_pk_fma_f32 v[156:157], v[124:125], v[232:233], v[86:87] op_sel_hi:[1,0,1]
	v_pk_fma_f32 v[158:159], v[126:127], v[232:233], v[76:77] op_sel_hi:[1,0,1]
	v_pk_fma_f32 v[104:105], v[60:61], v[230:231], v[118:119] op_sel_hi:[1,0,1]
	v_pk_fma_f32 v[110:111], v[68:69], v[230:231], v[116:117] op_sel_hi:[1,0,1]
	v_pk_fma_f32 v[98:99], v[60:61], v[230:231], v[98:99] op_sel:[0,1,0]
	v_pk_fma_f32 v[116:117], v[60:61], v[232:233], v[90:91] op_sel_hi:[1,0,1]
	v_pk_fma_f32 v[124:125], v[60:61], v[162:163], v[72:73] op_sel_hi:[1,0,1]
	v_pk_fma_f32 v[126:127], v[68:69], v[162:163], v[62:63] op_sel_hi:[1,0,1]
	v_cvt_pk_f32_fp8_e32 v[60:61], v228
	v_cvt_pk_f32_fp8_sdwa v[62:63], v228 src0_sel:WORD_1
	v_pk_fma_f32 v[112:113], v[68:69], v[230:231], v[96:97] op_sel:[0,1,0]
	v_pk_fma_f32 v[118:119], v[68:69], v[232:233], v[78:79] op_sel_hi:[1,0,1]
	v_pk_fma_f32 v[86:87], v[60:61], v[230:231], v[102:103] op_sel:[0,1,0]
	v_pk_fma_f32 v[90:91], v[62:63], v[230:231], v[100:101] op_sel:[0,1,0]
	v_cvt_pk_f32_fp8_e32 v[100:101], v229
	v_cvt_pk_f32_fp8_sdwa v[102:103], v229 src0_sel:WORD_1
	v_pk_fma_f32 v[76:77], v[60:61], v[230:231], v[120:121] op_sel_hi:[1,0,1]
	v_pk_fma_f32 v[78:79], v[62:63], v[230:231], v[108:109] op_sel_hi:[1,0,1]
	v_pk_fma_f32 v[82:83], v[60:61], v[232:233], v[82:83] op_sel_hi:[1,0,1]
	v_pk_fma_f32 v[80:81], v[62:63], v[232:233], v[80:81] op_sel_hi:[1,0,1]
	v_pk_fma_f32 v[92:93], v[60:61], v[162:163], v[74:75] op_sel_hi:[1,0,1]
	v_pk_fma_f32 v[96:97], v[62:63], v[162:163], v[64:65] op_sel_hi:[1,0,1]
	v_pk_fma_f32 v[60:61], v[100:101], v[230:231], v[122:123] op_sel_hi:[1,0,1]
	v_pk_fma_f32 v[62:63], v[102:103], v[230:231], v[114:115] op_sel_hi:[1,0,1]
	v_pk_fma_f32 v[64:65], v[100:101], v[230:231], v[106:107] op_sel:[0,1,0]
	v_pk_fma_f32 v[68:69], v[102:103], v[230:231], v[94:95] op_sel:[0,1,0]
	v_pk_fma_f32 v[72:73], v[100:101], v[232:233], v[88:89] op_sel_hi:[1,0,1]
	v_pk_fma_f32 v[74:75], v[102:103], v[232:233], v[84:85] op_sel_hi:[1,0,1]
	v_pk_fma_f32 v[70:71], v[100:101], v[162:163], v[70:71] op_sel_hi:[1,0,1]
	v_pk_fma_f32 v[66:67], v[102:103], v[162:163], v[66:67] op_sel_hi:[1,0,1]
	ds_read_b128 v[100:103], v225 offset:128
	s_waitcnt vmcnt(14)
	v_cvt_pk_f32_fp8_sdwa v[94:95], v56 src0_sel:WORD_1
	v_cvt_pk_f32_fp8_e32 v[88:89], v56
	s_waitcnt lgkmcnt(0)
	v_pk_fma_f32 v[108:109], v[94:95], v[100:101], v[150:151] op_sel_hi:[1,0,1]
	v_cvt_pk_f32_fp8_e32 v[150:151], v57
	v_pk_fma_f32 v[114:115], v[88:89], v[100:101], v[152:153] op_sel:[0,1,0]
	v_cvt_pk_f32_fp8_sdwa v[56:57], v57 src0_sel:WORD_1
	v_mov_b32_e32 v84, v103
	v_pk_fma_f32 v[152:153], v[150:151], v[100:101], v[104:105] op_sel_hi:[1,0,1]
	v_cvt_pk_f32_fp8_e32 v[104:105], v58
	v_pk_fma_f32 v[120:121], v[94:95], v[100:101], v[154:155] op_sel:[0,1,0]
	v_pk_fma_f32 v[122:123], v[88:89], v[102:103], v[156:157] op_sel_hi:[1,0,1]
	v_pk_fma_f32 v[154:155], v[56:57], v[100:101], v[110:111] op_sel_hi:[1,0,1]
	v_pk_fma_f32 v[156:157], v[56:57], v[100:101], v[112:113] op_sel:[0,1,0]
	v_pk_fma_f32 v[118:119], v[56:57], v[102:103], v[118:119] op_sel_hi:[1,0,1]
	v_pk_fma_f32 v[56:57], v[56:57], v[84:85], v[126:127] op_sel_hi:[1,0,1]
	v_cvt_pk_f32_fp8_sdwa v[110:111], v58 src0_sel:WORD_1
	v_pk_fma_f32 v[126:127], v[104:105], v[100:101], v[86:87] op_sel:[0,1,0]
	v_cvt_pk_f32_fp8_e32 v[86:87], v59
	v_cvt_pk_f32_fp8_sdwa v[58:59], v59 src0_sel:WORD_1
	v_pk_fma_f32 v[106:107], v[88:89], v[100:101], v[148:149] op_sel_hi:[1,0,1]
	v_pk_fma_f32 v[148:149], v[94:95], v[102:103], v[158:159] op_sel_hi:[1,0,1]
	v_pk_fma_f32 v[94:95], v[94:95], v[84:85], v[186:187] op_sel_hi:[1,0,1]
	v_pk_fma_f32 v[186:187], v[86:87], v[100:101], v[60:61] op_sel_hi:[1,0,1]
	v_pk_fma_f32 v[226:227], v[58:59], v[100:101], v[62:63] op_sel_hi:[1,0,1]
	ds_read_b128 v[60:63], v225 offset:256
	v_pk_fma_f32 v[228:229], v[58:59], v[100:101], v[68:69] op_sel:[0,1,0]
	v_pk_fma_f32 v[232:233], v[58:59], v[102:103], v[74:75] op_sel_hi:[1,0,1]
	v_pk_fma_f32 v[66:67], v[58:59], v[84:85], v[66:67] op_sel_hi:[1,0,1]
	s_waitcnt vmcnt(13)
	v_cvt_pk_f32_fp8_e32 v[58:59], v52
	v_cvt_pk_f32_fp8_sdwa v[68:69], v52 src0_sel:WORD_1
	v_pk_fma_f32 v[88:89], v[88:89], v[84:85], v[184:185] op_sel_hi:[1,0,1]
	s_waitcnt lgkmcnt(0)
; __device__ __forceinline__ void dsa_attend(const h16* PROJ, const unsigned short* IDX, const int* CNT, h16* MIXA, unsigned char* shm, unsigned* bar, unsigned xcc, unsigned xrank) {
;     ...
;                 for (int e = 0; e < 16; ++e) { const int slot = s0 + 8 * e + r8;
;                     if ((e & 3) == 0) __builtin_amdgcn_sched_barrier(0);
;                     const f32x4 pp = *(const f32x4*)(Pl + ((size_t)wid * 256 + slot) * 4);
;                     const f32x2 p0 = (f32x2){pp.x, pp.x}, p1 = (f32x2){pp.y, pp.y}, p2 = (f32x2){pp.z, pp.z}, p3 = (f32x2){pp.w, pp.w};
;                     const unsigned wds[4] = {vv[e].x, vv[e].y, vv[e].z, vv[e].w};
; #pragma unroll
;                     for (int w = 0; w < 4; ++w) {
;                         const f32x2 lo = __builtin_amdgcn_cvt_pk_f32_fp8((int)wds[w], false), hi = __builtin_amdgcn_cvt_pk_f32_fp8((int)wds[w], true);
;                         oa2[0][2 * w] = __builtin_elementwise_fma(lo, p0, oa2[0][2 * w]); oa2[0][2 * w + 1] = __builtin_elementwise_fma(hi, p0, oa2[0][2 * w + 1]);
;                         oa2[1][2 * w] = __builtin_elementwise_fma(lo, p1, oa2[1][2 * w]); oa2[1][2 * w + 1] = __builtin_elementwise_fma(hi, p1, oa2[1][2 * w + 1]);
;                         oa2[2][2 * w] = __builtin_elementwise_fma(lo, p2, oa2[2][2 * w]); oa2[2][2 * w + 1] = __builtin_elementwise_fma(hi, p2, oa2[2][2 * w + 1]);
;                         oa2[3][2 * w] = __builtin_elementwise_fma(lo, p3, oa2[3][2 * w]); oa2[3][2 * w + 1] = __builtin_elementwise_fma(hi, p3, oa2[3][2 * w + 1]); }
	v_mov_b32_e32 v162, v63
	v_pk_fma_f32 v[98:99], v[150:151], v[100:101], v[98:99] op_sel:[0,1,0]
	v_pk_fma_f32 v[116:117], v[150:151], v[102:103], v[116:117] op_sel_hi:[1,0,1]
	v_pk_fma_f32 v[124:125], v[150:151], v[84:85], v[124:125] op_sel_hi:[1,0,1]
	v_pk_fma_f32 v[76:77], v[104:105], v[100:101], v[76:77] op_sel_hi:[1,0,1]
	v_pk_fma_f32 v[78:79], v[110:111], v[100:101], v[78:79] op_sel_hi:[1,0,1]
	v_pk_fma_f32 v[150:151], v[110:111], v[100:101], v[90:91] op_sel:[0,1,0]
	v_pk_fma_f32 v[82:83], v[104:105], v[102:103], v[82:83] op_sel_hi:[1,0,1]
	v_pk_fma_f32 v[80:81], v[110:111], v[102:103], v[80:81] op_sel_hi:[1,0,1]
	v_pk_fma_f32 v[158:159], v[104:105], v[84:85], v[92:93] op_sel_hi:[1,0,1]
	v_pk_fma_f32 v[64:65], v[86:87], v[100:101], v[64:65] op_sel:[0,1,0]
	v_pk_fma_f32 v[230:231], v[86:87], v[102:103], v[72:73] op_sel_hi:[1,0,1]
	v_pk_fma_f32 v[100:101], v[58:59], v[60:61], v[106:107] op_sel_hi:[1,0,1]
	v_pk_fma_f32 v[102:103], v[68:69], v[60:61], v[108:109] op_sel_hi:[1,0,1]
	v_pk_fma_f32 v[104:105], v[58:59], v[60:61], v[114:115] op_sel:[0,1,0]
	v_pk_fma_f32 v[108:109], v[58:59], v[62:63], v[122:123] op_sel_hi:[1,0,1]
	v_pk_fma_f32 v[112:113], v[58:59], v[162:163], v[88:89] op_sel_hi:[1,0,1]
	v_cvt_pk_f32_fp8_e32 v[58:59], v53
	v_cvt_pk_f32_fp8_sdwa v[52:53], v53 src0_sel:WORD_1
	v_pk_fma_f32 v[234:235], v[86:87], v[84:85], v[70:71] op_sel_hi:[1,0,1]
	v_pk_fma_f32 v[114:115], v[68:69], v[162:163], v[94:95] op_sel_hi:[1,0,1]
	v_pk_fma_f32 v[88:89], v[58:59], v[60:61], v[98:99] op_sel:[0,1,0]
	v_pk_fma_f32 v[86:87], v[52:53], v[60:61], v[154:155] op_sel_hi:[1,0,1]
	v_pk_fma_f32 v[90:91], v[52:53], v[60:61], v[156:157] op_sel:[0,1,0]
	v_pk_fma_f32 v[92:93], v[58:59], v[62:63], v[116:117] op_sel_hi:[1,0,1]
	v_pk_fma_f32 v[94:95], v[52:53], v[62:63], v[118:119] op_sel_hi:[1,0,1]
	v_pk_fma_f32 v[98:99], v[52:53], v[162:163], v[56:57] op_sel_hi:[1,0,1]
	v_cvt_pk_f32_fp8_e32 v[52:53], v54
	v_cvt_pk_f32_fp8_sdwa v[56:57], v54 src0_sel:WORD_1
	v_cvt_pk_f32_fp8_e32 v[116:117], v55
	v_cvt_pk_f32_fp8_sdwa v[118:119], v55 src0_sel:WORD_1
	v_pk_fma_f32 v[184:185], v[110:111], v[84:85], v[96:97] op_sel_hi:[1,0,1]
	v_pk_fma_f32 v[106:107], v[68:69], v[60:61], v[120:121] op_sel:[0,1,0]
	v_pk_fma_f32 v[110:111], v[68:69], v[62:63], v[148:149] op_sel_hi:[1,0,1]
	v_pk_fma_f32 v[84:85], v[58:59], v[60:61], v[152:153] op_sel_hi:[1,0,1]
	v_pk_fma_f32 v[96:97], v[58:59], v[162:163], v[124:125] op_sel_hi:[1,0,1]
	v_pk_fma_f32 v[68:69], v[52:53], v[60:61], v[76:77] op_sel_hi:[1,0,1]
	v_pk_fma_f32 v[70:71], v[56:57], v[60:61], v[78:79] op_sel_hi:[1,0,1]
	v_pk_fma_f32 v[72:73], v[52:53], v[60:61], v[126:127] op_sel:[0,1,0]
	v_pk_fma_f32 v[74:75], v[56:57], v[60:61], v[150:151] op_sel:[0,1,0]
	v_pk_fma_f32 v[76:77], v[52:53], v[62:63], v[82:83] op_sel_hi:[1,0,1]
	v_pk_fma_f32 v[78:79], v[56:57], v[62:63], v[80:81] op_sel_hi:[1,0,1]
	v_pk_fma_f32 v[80:81], v[52:53], v[162:163], v[158:159] op_sel_hi:[1,0,1]
	v_pk_fma_f32 v[82:83], v[56:57], v[162:163], v[184:185] op_sel_hi:[1,0,1]
	v_pk_fma_f32 v[52:53], v[116:117], v[60:61], v[186:187] op_sel_hi:[1,0,1]
	v_pk_fma_f32 v[54:55], v[118:119], v[60:61], v[226:227] op_sel_hi:[1,0,1]
	v_pk_fma_f32 v[56:57], v[116:117], v[60:61], v[64:65] op_sel:[0,1,0]
	v_pk_fma_f32 v[58:59], v[118:119], v[60:61], v[228:229] op_sel:[0,1,0]
	v_pk_fma_f32 v[60:61], v[116:117], v[62:63], v[230:231] op_sel_hi:[1,0,1]
	v_pk_fma_f32 v[62:63], v[118:119], v[62:63], v[232:233] op_sel_hi:[1,0,1]
	v_pk_fma_f32 v[64:65], v[116:117], v[162:163], v[234:235] op_sel_hi:[1,0,1]
	v_pk_fma_f32 v[66:67], v[118:119], v[162:163], v[66:67] op_sel_hi:[1,0,1]
	ds_read_b128 v[116:119], v225 offset:384
	s_waitcnt vmcnt(12)
	v_cvt_pk_f32_fp8_e32 v[122:123], v48
	v_cvt_pk_f32_fp8_sdwa v[124:125], v48 src0_sel:WORD_1
	s_waitcnt lgkmcnt(0)
	v_mov_b32_e32 v120, v119
	v_pk_fma_f32 v[100:101], v[122:123], v[116:117], v[100:101] op_sel_hi:[1,0,1]
	v_pk_fma_f32 v[104:105], v[122:123], v[116:117], v[104:105] op_sel:[0,1,0]
	v_pk_fma_f32 v[108:109], v[122:123], v[118:119], v[108:109] op_sel_hi:[1,0,1]
	v_pk_fma_f32 v[112:113], v[122:123], v[120:121], v[112:113] op_sel_hi:[1,0,1]
	v_cvt_pk_f32_fp8_e32 v[122:123], v49
	v_pk_fma_f32 v[102:103], v[124:125], v[116:117], v[102:103] op_sel_hi:[1,0,1]
	v_pk_fma_f32 v[106:107], v[124:125], v[116:117], v[106:107] op_sel:[0,1,0]
	v_pk_fma_f32 v[110:111], v[124:125], v[118:119], v[110:111] op_sel_hi:[1,0,1]
	v_pk_fma_f32 v[114:115], v[124:125], v[120:121], v[114:115] op_sel_hi:[1,0,1]
	v_cvt_pk_f32_fp8_sdwa v[48:49], v49 src0_sel:WORD_1
	v_pk_fma_f32 v[124:125], v[122:123], v[118:119], v[92:93] op_sel_hi:[1,0,1]
	v_cvt_pk_f32_fp8_e32 v[92:93], v50
	v_pk_fma_f32 v[84:85], v[122:123], v[116:117], v[84:85] op_sel_hi:[1,0,1]
	v_pk_fma_f32 v[126:127], v[48:49], v[118:119], v[94:95] op_sel_hi:[1,0,1]
	v_cvt_pk_f32_fp8_sdwa v[94:95], v50 src0_sel:WORD_1
	v_pk_fma_f32 v[148:149], v[92:93], v[118:119], v[76:77] op_sel_hi:[1,0,1]
	v_cvt_pk_f32_fp8_e32 v[76:77], v51
	v_cvt_pk_f32_fp8_sdwa v[50:51], v51 src0_sel:WORD_1
	v_pk_fma_f32 v[86:87], v[48:49], v[116:117], v[86:87] op_sel_hi:[1,0,1]
	v_pk_fma_f32 v[88:89], v[122:123], v[116:117], v[88:89] op_sel:[0,1,0]
	v_pk_fma_f32 v[90:91], v[48:49], v[116:117], v[90:91] op_sel:[0,1,0]
	v_pk_fma_f32 v[122:123], v[122:123], v[120:121], v[96:97] op_sel_hi:[1,0,1]
	v_pk_fma_f32 v[48:49], v[48:49], v[120:121], v[98:99] op_sel_hi:[1,0,1]
	v_pk_fma_f32 v[68:69], v[92:93], v[116:117], v[68:69] op_sel_hi:[1,0,1]
	v_pk_fma_f32 v[70:71], v[94:95], v[116:117], v[70:71] op_sel_hi:[1,0,1]
	v_pk_fma_f32 v[72:73], v[92:93], v[116:117], v[72:73] op_sel:[0,1,0]
	v_pk_fma_f32 v[74:75], v[94:95], v[116:117], v[74:75] op_sel:[0,1,0]
	v_pk_fma_f32 v[150:151], v[94:95], v[118:119], v[78:79] op_sel_hi:[1,0,1]
	v_pk_fma_f32 v[152:153], v[92:93], v[120:121], v[80:81] op_sel_hi:[1,0,1]
	v_pk_fma_f32 v[154:155], v[94:95], v[120:121], v[82:83] op_sel_hi:[1,0,1]
	v_pk_fma_f32 v[156:157], v[76:77], v[116:117], v[52:53] op_sel_hi:[1,0,1]
	v_pk_fma_f32 v[158:159], v[50:51], v[116:117], v[54:55] op_sel_hi:[1,0,1]
	v_pk_fma_f32 v[56:57], v[76:77], v[116:117], v[56:57] op_sel:[0,1,0]
	v_pk_fma_f32 v[58:59], v[50:51], v[116:117], v[58:59] op_sel:[0,1,0]
	v_pk_fma_f32 v[116:117], v[76:77], v[118:119], v[60:61] op_sel_hi:[1,0,1]
	v_pk_fma_f32 v[118:119], v[50:51], v[118:119], v[62:63] op_sel_hi:[1,0,1]
	v_pk_fma_f32 v[184:185], v[76:77], v[120:121], v[64:65] op_sel_hi:[1,0,1]
	v_pk_fma_f32 v[120:121], v[50:51], v[120:121], v[66:67] op_sel_hi:[1,0,1]
	ds_read_b128 v[52:55], v225 offset:512
	s_waitcnt vmcnt(11)
; __device__ __forceinline__ void dsa_attend(const h16* PROJ, const unsigned short* IDX, const int* CNT, h16* MIXA, unsigned char* shm, unsigned* bar, unsigned xcc, unsigned xrank) {
;     ...
;                 for (int e = 0; e < 16; ++e) { const int slot = s0 + 8 * e + r8;
;                     if ((e & 3) == 0) __builtin_amdgcn_sched_barrier(0);
;                     const f32x4 pp = *(const f32x4*)(Pl + ((size_t)wid * 256 + slot) * 4);
;                     const f32x2 p0 = (f32x2){pp.x, pp.x}, p1 = (f32x2){pp.y, pp.y}, p2 = (f32x2){pp.z, pp.z}, p3 = (f32x2){pp.w, pp.w};
;                     const unsigned wds[4] = {vv[e].x, vv[e].y, vv[e].z, vv[e].w};
; #pragma unroll
;                     for (int w = 0; w < 4; ++w) {
;                         const f32x2 lo = __builtin_amdgcn_cvt_pk_f32_fp8((int)wds[w], false), hi = __builtin_amdgcn_cvt_pk_f32_fp8((int)wds[w], true);
;                         oa2[0][2 * w] = __builtin_elementwise_fma(lo, p0, oa2[0][2 * w]); oa2[0][2 * w + 1] = __builtin_elementwise_fma(hi, p0, oa2[0][2 * w + 1]);
;                         oa2[1][2 * w] = __builtin_elementwise_fma(lo, p1, oa2[1][2 * w]); oa2[1][2 * w + 1] = __builtin_elementwise_fma(hi, p1, oa2[1][2 * w + 1]);
;                         oa2[2][2 * w] = __builtin_elementwise_fma(lo, p2, oa2[2][2 * w]); oa2[2][2 * w + 1] = __builtin_elementwise_fma(hi, p2, oa2[2][2 * w + 1]);
;                         oa2[3][2 * w] = __builtin_elementwise_fma(lo, p3, oa2[3][2 * w]); oa2[3][2 * w + 1] = __builtin_elementwise_fma(hi, p3, oa2[3][2 * w + 1]); }
	v_cvt_pk_f32_fp8_e32 v[50:51], v44
	v_cvt_pk_f32_fp8_sdwa v[60:61], v44 src0_sel:WORD_1
	s_waitcnt lgkmcnt(0)
	v_mov_b32_e32 v162, v55
	v_pk_fma_f32 v[92:93], v[50:51], v[52:53], v[100:101] op_sel_hi:[1,0,1]
	v_pk_fma_f32 v[96:97], v[50:51], v[52:53], v[104:105] op_sel:[0,1,0]
	v_pk_fma_f32 v[100:101], v[50:51], v[54:55], v[108:109] op_sel_hi:[1,0,1]
	v_pk_fma_f32 v[104:105], v[50:51], v[162:163], v[112:113] op_sel_hi:[1,0,1]
	v_cvt_pk_f32_fp8_e32 v[50:51], v45
	v_cvt_pk_f32_fp8_sdwa v[44:45], v45 src0_sel:WORD_1
	v_pk_fma_f32 v[94:95], v[60:61], v[52:53], v[102:103] op_sel_hi:[1,0,1]
	v_pk_fma_f32 v[102:103], v[60:61], v[54:55], v[110:111] op_sel_hi:[1,0,1]
	v_cvt_pk_f32_fp8_e32 v[108:109], v47
	v_pk_fma_f32 v[78:79], v[44:45], v[52:53], v[86:87] op_sel_hi:[1,0,1]
	v_pk_fma_f32 v[82:83], v[44:45], v[52:53], v[90:91] op_sel:[0,1,0]
	v_pk_fma_f32 v[86:87], v[44:45], v[54:55], v[126:127] op_sel_hi:[1,0,1]
	v_pk_fma_f32 v[90:91], v[44:45], v[162:163], v[48:49] op_sel_hi:[1,0,1]
	v_cvt_pk_f32_fp8_e32 v[44:45], v46
	v_cvt_pk_f32_fp8_sdwa v[48:49], v46 src0_sel:WORD_1
	v_cvt_pk_f32_fp8_sdwa v[110:111], v47 src0_sel:WORD_1
	v_pk_fma_f32 v[98:99], v[60:61], v[52:53], v[106:107] op_sel:[0,1,0]
	v_pk_fma_f32 v[106:107], v[60:61], v[162:163], v[114:115] op_sel_hi:[1,0,1]
	v_pk_fma_f32 v[76:77], v[50:51], v[52:53], v[84:85] op_sel_hi:[1,0,1]
	v_pk_fma_f32 v[80:81], v[50:51], v[52:53], v[88:89] op_sel:[0,1,0]
	v_pk_fma_f32 v[84:85], v[50:51], v[54:55], v[124:125] op_sel_hi:[1,0,1]
	v_pk_fma_f32 v[88:89], v[50:51], v[162:163], v[122:123] op_sel_hi:[1,0,1]
	v_pk_fma_f32 v[60:61], v[44:45], v[52:53], v[68:69] op_sel_hi:[1,0,1]
	v_pk_fma_f32 v[62:63], v[48:49], v[52:53], v[70:71] op_sel_hi:[1,0,1]
	v_pk_fma_f32 v[64:65], v[44:45], v[52:53], v[72:73] op_sel:[0,1,0]
	v_pk_fma_f32 v[66:67], v[48:49], v[52:53], v[74:75] op_sel:[0,1,0]
	v_pk_fma_f32 v[68:69], v[44:45], v[54:55], v[148:149] op_sel_hi:[1,0,1]
	v_pk_fma_f32 v[70:71], v[48:49], v[54:55], v[150:151] op_sel_hi:[1,0,1]
	v_pk_fma_f32 v[72:73], v[44:45], v[162:163], v[152:153] op_sel_hi:[1,0,1]
	v_pk_fma_f32 v[74:75], v[48:49], v[162:163], v[154:155] op_sel_hi:[1,0,1]
	v_pk_fma_f32 v[44:45], v[108:109], v[52:53], v[156:157] op_sel_hi:[1,0,1]
	v_pk_fma_f32 v[46:47], v[110:111], v[52:53], v[158:159] op_sel_hi:[1,0,1]
	v_pk_fma_f32 v[48:49], v[108:109], v[52:53], v[56:57] op_sel:[0,1,0]
	v_pk_fma_f32 v[50:51], v[110:111], v[52:53], v[58:59] op_sel:[0,1,0]
	v_pk_fma_f32 v[52:53], v[108:109], v[54:55], v[116:117] op_sel_hi:[1,0,1]
	v_pk_fma_f32 v[54:55], v[110:111], v[54:55], v[118:119] op_sel_hi:[1,0,1]
	v_pk_fma_f32 v[56:57], v[108:109], v[162:163], v[184:185] op_sel_hi:[1,0,1]
	v_pk_fma_f32 v[58:59], v[110:111], v[162:163], v[120:121] op_sel_hi:[1,0,1]
	ds_read_b128 v[108:111], v225 offset:640
	s_waitcnt vmcnt(10)
	v_cvt_pk_f32_fp8_e32 v[114:115], v40
	v_cvt_pk_f32_fp8_sdwa v[116:117], v40 src0_sel:WORD_1
	s_waitcnt lgkmcnt(0)
	v_mov_b32_e32 v112, v111
	v_pk_fma_f32 v[92:93], v[114:115], v[108:109], v[92:93] op_sel_hi:[1,0,1]
	v_pk_fma_f32 v[96:97], v[114:115], v[108:109], v[96:97] op_sel:[0,1,0]
	v_pk_fma_f32 v[100:101], v[114:115], v[110:111], v[100:101] op_sel_hi:[1,0,1]
	v_pk_fma_f32 v[104:105], v[114:115], v[112:113], v[104:105] op_sel_hi:[1,0,1]
	v_cvt_pk_f32_fp8_e32 v[114:115], v41
	v_pk_fma_f32 v[94:95], v[116:117], v[108:109], v[94:95] op_sel_hi:[1,0,1]
	v_pk_fma_f32 v[98:99], v[116:117], v[108:109], v[98:99] op_sel:[0,1,0]
	v_pk_fma_f32 v[102:103], v[116:117], v[110:111], v[102:103] op_sel_hi:[1,0,1]
	v_pk_fma_f32 v[106:107], v[116:117], v[112:113], v[106:107] op_sel_hi:[1,0,1]
	v_cvt_pk_f32_fp8_sdwa v[40:41], v41 src0_sel:WORD_1
	v_pk_fma_f32 v[116:117], v[114:115], v[110:111], v[84:85] op_sel_hi:[1,0,1]
	v_cvt_pk_f32_fp8_e32 v[84:85], v42
	v_pk_fma_f32 v[76:77], v[114:115], v[108:109], v[76:77] op_sel_hi:[1,0,1]
	v_pk_fma_f32 v[118:119], v[40:41], v[110:111], v[86:87] op_sel_hi:[1,0,1]
	v_cvt_pk_f32_fp8_sdwa v[86:87], v42 src0_sel:WORD_1
	v_pk_fma_f32 v[120:121], v[84:85], v[110:111], v[68:69] op_sel_hi:[1,0,1]
	v_cvt_pk_f32_fp8_e32 v[68:69], v43
	v_cvt_pk_f32_fp8_sdwa v[42:43], v43 src0_sel:WORD_1
	v_pk_fma_f32 v[78:79], v[40:41], v[108:109], v[78:79] op_sel_hi:[1,0,1]
	v_pk_fma_f32 v[80:81], v[114:115], v[108:109], v[80:81] op_sel:[0,1,0]
	v_pk_fma_f32 v[148:149], v[68:69], v[108:109], v[44:45] op_sel_hi:[1,0,1]
	v_pk_fma_f32 v[150:151], v[42:43], v[108:109], v[46:47] op_sel_hi:[1,0,1]
	ds_read_b128 v[44:47], v225 offset:768
	v_pk_fma_f32 v[82:83], v[40:41], v[108:109], v[82:83] op_sel:[0,1,0]
	v_pk_fma_f32 v[114:115], v[114:115], v[112:113], v[88:89] op_sel_hi:[1,0,1]
	v_pk_fma_f32 v[40:41], v[40:41], v[112:113], v[90:91] op_sel_hi:[1,0,1]
	v_pk_fma_f32 v[60:61], v[84:85], v[108:109], v[60:61] op_sel_hi:[1,0,1]
	v_pk_fma_f32 v[62:63], v[86:87], v[108:109], v[62:63] op_sel_hi:[1,0,1]
	v_pk_fma_f32 v[64:65], v[84:85], v[108:109], v[64:65] op_sel:[0,1,0]
	v_pk_fma_f32 v[66:67], v[86:87], v[108:109], v[66:67] op_sel:[0,1,0]
	v_pk_fma_f32 v[122:123], v[86:87], v[110:111], v[70:71] op_sel_hi:[1,0,1]
	v_pk_fma_f32 v[124:125], v[84:85], v[112:113], v[72:73] op_sel_hi:[1,0,1]
	v_pk_fma_f32 v[126:127], v[86:87], v[112:113], v[74:75] op_sel_hi:[1,0,1]
	v_pk_fma_f32 v[48:49], v[68:69], v[108:109], v[48:49] op_sel:[0,1,0]
	v_pk_fma_f32 v[50:51], v[42:43], v[108:109], v[50:51] op_sel:[0,1,0]
	v_pk_fma_f32 v[108:109], v[68:69], v[110:111], v[52:53] op_sel_hi:[1,0,1]
	v_pk_fma_f32 v[110:111], v[42:43], v[110:111], v[54:55] op_sel_hi:[1,0,1]
	v_pk_fma_f32 v[152:153], v[68:69], v[112:113], v[56:57] op_sel_hi:[1,0,1]
	v_pk_fma_f32 v[112:113], v[42:43], v[112:113], v[58:59] op_sel_hi:[1,0,1]
	s_waitcnt vmcnt(9)
; __device__ __forceinline__ void dsa_attend(const h16* PROJ, const unsigned short* IDX, const int* CNT, h16* MIXA, unsigned char* shm, unsigned* bar, unsigned xcc, unsigned xrank) {
;     ...
;                 for (int e = 0; e < 16; ++e) { const int slot = s0 + 8 * e + r8;
;                     if ((e & 3) == 0) __builtin_amdgcn_sched_barrier(0);
;                     const f32x4 pp = *(const f32x4*)(Pl + ((size_t)wid * 256 + slot) * 4);
;                     const f32x2 p0 = (f32x2){pp.x, pp.x}, p1 = (f32x2){pp.y, pp.y}, p2 = (f32x2){pp.z, pp.z}, p3 = (f32x2){pp.w, pp.w};
;                     const unsigned wds[4] = {vv[e].x, vv[e].y, vv[e].z, vv[e].w};
; #pragma unroll
;                     for (int w = 0; w < 4; ++w) {
;                         const f32x2 lo = __builtin_amdgcn_cvt_pk_f32_fp8((int)wds[w], false), hi = __builtin_amdgcn_cvt_pk_f32_fp8((int)wds[w], true);
;                         oa2[0][2 * w] = __builtin_elementwise_fma(lo, p0, oa2[0][2 * w]); oa2[0][2 * w + 1] = __builtin_elementwise_fma(hi, p0, oa2[0][2 * w + 1]);
;                         oa2[1][2 * w] = __builtin_elementwise_fma(lo, p1, oa2[1][2 * w]); oa2[1][2 * w + 1] = __builtin_elementwise_fma(hi, p1, oa2[1][2 * w + 1]);
;                         oa2[2][2 * w] = __builtin_elementwise_fma(lo, p2, oa2[2][2 * w]); oa2[2][2 * w + 1] = __builtin_elementwise_fma(hi, p2, oa2[2][2 * w + 1]);
;                         oa2[3][2 * w] = __builtin_elementwise_fma(lo, p3, oa2[3][2 * w]); oa2[3][2 * w + 1] = __builtin_elementwise_fma(hi, p3, oa2[3][2 * w + 1]); }
	v_cvt_pk_f32_fp8_e32 v[42:43], v36
	s_waitcnt lgkmcnt(0)
	v_mov_b32_e32 v154, v47
	v_cvt_pk_f32_fp8_sdwa v[52:53], v36 src0_sel:WORD_1
	v_pk_fma_f32 v[84:85], v[42:43], v[44:45], v[92:93] op_sel_hi:[1,0,1]
	v_pk_fma_f32 v[88:89], v[42:43], v[44:45], v[96:97] op_sel:[0,1,0]
	v_pk_fma_f32 v[92:93], v[42:43], v[46:47], v[100:101] op_sel_hi:[1,0,1]
	v_pk_fma_f32 v[96:97], v[42:43], v[154:155], v[104:105] op_sel_hi:[1,0,1]
	v_cvt_pk_f32_fp8_e32 v[42:43], v37
	v_cvt_pk_f32_fp8_sdwa v[36:37], v37 src0_sel:WORD_1
	v_pk_fma_f32 v[86:87], v[52:53], v[44:45], v[94:95] op_sel_hi:[1,0,1]
	v_pk_fma_f32 v[94:95], v[52:53], v[46:47], v[102:103] op_sel_hi:[1,0,1]
	v_cvt_pk_f32_fp8_e32 v[100:101], v39
	v_pk_fma_f32 v[70:71], v[36:37], v[44:45], v[78:79] op_sel_hi:[1,0,1]
	v_pk_fma_f32 v[74:75], v[36:37], v[44:45], v[82:83] op_sel:[0,1,0]
	v_pk_fma_f32 v[78:79], v[36:37], v[46:47], v[118:119] op_sel_hi:[1,0,1]
	v_pk_fma_f32 v[82:83], v[36:37], v[154:155], v[40:41] op_sel_hi:[1,0,1]
	v_cvt_pk_f32_fp8_e32 v[36:37], v38
	v_cvt_pk_f32_fp8_sdwa v[40:41], v38 src0_sel:WORD_1
	v_cvt_pk_f32_fp8_sdwa v[102:103], v39 src0_sel:WORD_1
	v_pk_fma_f32 v[90:91], v[52:53], v[44:45], v[98:99] op_sel:[0,1,0]
	v_pk_fma_f32 v[98:99], v[52:53], v[154:155], v[106:107] op_sel_hi:[1,0,1]
	v_pk_fma_f32 v[68:69], v[42:43], v[44:45], v[76:77] op_sel_hi:[1,0,1]
	v_pk_fma_f32 v[72:73], v[42:43], v[44:45], v[80:81] op_sel:[0,1,0]
	v_pk_fma_f32 v[76:77], v[42:43], v[46:47], v[116:117] op_sel_hi:[1,0,1]
	v_pk_fma_f32 v[80:81], v[42:43], v[154:155], v[114:115] op_sel_hi:[1,0,1]
	v_pk_fma_f32 v[52:53], v[36:37], v[44:45], v[60:61] op_sel_hi:[1,0,1]
	v_pk_fma_f32 v[54:55], v[40:41], v[44:45], v[62:63] op_sel_hi:[1,0,1]
	v_pk_fma_f32 v[56:57], v[36:37], v[44:45], v[64:65] op_sel:[0,1,0]
	v_pk_fma_f32 v[58:59], v[40:41], v[44:45], v[66:67] op_sel:[0,1,0]
	v_pk_fma_f32 v[60:61], v[36:37], v[46:47], v[120:121] op_sel_hi:[1,0,1]
	v_pk_fma_f32 v[62:63], v[40:41], v[46:47], v[122:123] op_sel_hi:[1,0,1]
	v_pk_fma_f32 v[64:65], v[36:37], v[154:155], v[124:125] op_sel_hi:[1,0,1]
	v_pk_fma_f32 v[66:67], v[40:41], v[154:155], v[126:127] op_sel_hi:[1,0,1]
	v_pk_fma_f32 v[36:37], v[100:101], v[44:45], v[148:149] op_sel_hi:[1,0,1]
	v_pk_fma_f32 v[38:39], v[102:103], v[44:45], v[150:151] op_sel_hi:[1,0,1]
	v_pk_fma_f32 v[40:41], v[100:101], v[44:45], v[48:49] op_sel:[0,1,0]
	v_pk_fma_f32 v[42:43], v[102:103], v[44:45], v[50:51] op_sel:[0,1,0]
	v_pk_fma_f32 v[44:45], v[100:101], v[46:47], v[108:109] op_sel_hi:[1,0,1]
	v_pk_fma_f32 v[46:47], v[102:103], v[46:47], v[110:111] op_sel_hi:[1,0,1]
	v_pk_fma_f32 v[48:49], v[100:101], v[154:155], v[152:153] op_sel_hi:[1,0,1]
	v_pk_fma_f32 v[50:51], v[102:103], v[154:155], v[112:113] op_sel_hi:[1,0,1]
	ds_read_b128 v[100:103], v225 offset:896
	s_waitcnt vmcnt(8)
	v_cvt_pk_f32_fp8_e32 v[106:107], v28
	v_cvt_pk_f32_fp8_sdwa v[108:109], v28 src0_sel:WORD_1
	s_waitcnt lgkmcnt(0)
	v_mov_b32_e32 v104, v103
	v_pk_fma_f32 v[84:85], v[106:107], v[100:101], v[84:85] op_sel_hi:[1,0,1]
	v_pk_fma_f32 v[88:89], v[106:107], v[100:101], v[88:89] op_sel:[0,1,0]
	v_pk_fma_f32 v[92:93], v[106:107], v[102:103], v[92:93] op_sel_hi:[1,0,1]
	v_pk_fma_f32 v[96:97], v[106:107], v[104:105], v[96:97] op_sel_hi:[1,0,1]
	v_cvt_pk_f32_fp8_e32 v[106:107], v29
	v_pk_fma_f32 v[86:87], v[108:109], v[100:101], v[86:87] op_sel_hi:[1,0,1]
	v_pk_fma_f32 v[90:91], v[108:109], v[100:101], v[90:91] op_sel:[0,1,0]
	v_pk_fma_f32 v[94:95], v[108:109], v[102:103], v[94:95] op_sel_hi:[1,0,1]
	v_pk_fma_f32 v[98:99], v[108:109], v[104:105], v[98:99] op_sel_hi:[1,0,1]
	v_cvt_pk_f32_fp8_sdwa v[28:29], v29 src0_sel:WORD_1
	v_pk_fma_f32 v[108:109], v[106:107], v[102:103], v[76:77] op_sel_hi:[1,0,1]
	v_cvt_pk_f32_fp8_e32 v[76:77], v30
	v_pk_fma_f32 v[68:69], v[106:107], v[100:101], v[68:69] op_sel_hi:[1,0,1]
	v_pk_fma_f32 v[110:111], v[28:29], v[102:103], v[78:79] op_sel_hi:[1,0,1]
	v_cvt_pk_f32_fp8_sdwa v[78:79], v30 src0_sel:WORD_1
	v_pk_fma_f32 v[112:113], v[76:77], v[102:103], v[60:61] op_sel_hi:[1,0,1]
	v_cvt_pk_f32_fp8_e32 v[60:61], v31
	v_cvt_pk_f32_fp8_sdwa v[30:31], v31 src0_sel:WORD_1
	v_pk_fma_f32 v[70:71], v[28:29], v[100:101], v[70:71] op_sel_hi:[1,0,1]
	v_pk_fma_f32 v[72:73], v[106:107], v[100:101], v[72:73] op_sel:[0,1,0]
	v_pk_fma_f32 v[74:75], v[28:29], v[100:101], v[74:75] op_sel:[0,1,0]
	v_pk_fma_f32 v[106:107], v[106:107], v[104:105], v[80:81] op_sel_hi:[1,0,1]
	v_pk_fma_f32 v[28:29], v[28:29], v[104:105], v[82:83] op_sel_hi:[1,0,1]
	v_pk_fma_f32 v[52:53], v[76:77], v[100:101], v[52:53] op_sel_hi:[1,0,1]
	v_pk_fma_f32 v[54:55], v[78:79], v[100:101], v[54:55] op_sel_hi:[1,0,1]
	v_pk_fma_f32 v[56:57], v[76:77], v[100:101], v[56:57] op_sel:[0,1,0]
	v_pk_fma_f32 v[58:59], v[78:79], v[100:101], v[58:59] op_sel:[0,1,0]
	v_pk_fma_f32 v[114:115], v[78:79], v[102:103], v[62:63] op_sel_hi:[1,0,1]
	v_pk_fma_f32 v[116:117], v[76:77], v[104:105], v[64:65] op_sel_hi:[1,0,1]
	v_pk_fma_f32 v[118:119], v[78:79], v[104:105], v[66:67] op_sel_hi:[1,0,1]
	v_pk_fma_f32 v[120:121], v[60:61], v[100:101], v[36:37] op_sel_hi:[1,0,1]
	v_pk_fma_f32 v[122:123], v[30:31], v[100:101], v[38:39] op_sel_hi:[1,0,1]
	v_pk_fma_f32 v[40:41], v[60:61], v[100:101], v[40:41] op_sel:[0,1,0]
	v_pk_fma_f32 v[42:43], v[30:31], v[100:101], v[42:43] op_sel:[0,1,0]
	v_pk_fma_f32 v[100:101], v[60:61], v[102:103], v[44:45] op_sel_hi:[1,0,1]
	v_pk_fma_f32 v[102:103], v[30:31], v[102:103], v[46:47] op_sel_hi:[1,0,1]
	v_pk_fma_f32 v[124:125], v[60:61], v[104:105], v[48:49] op_sel_hi:[1,0,1]
	v_pk_fma_f32 v[104:105], v[30:31], v[104:105], v[50:51] op_sel_hi:[1,0,1]
	ds_read_b128 v[36:39], v225 offset:1024
	s_waitcnt vmcnt(7)
; __device__ __forceinline__ void dsa_attend(const h16* PROJ, const unsigned short* IDX, const int* CNT, h16* MIXA, unsigned char* shm, unsigned* bar, unsigned xcc, unsigned xrank) {
;     ...
;                 for (int e = 0; e < 16; ++e) { const int slot = s0 + 8 * e + r8;
;                     if ((e & 3) == 0) __builtin_amdgcn_sched_barrier(0);
;                     const f32x4 pp = *(const f32x4*)(Pl + ((size_t)wid * 256 + slot) * 4);
;                     const f32x2 p0 = (f32x2){pp.x, pp.x}, p1 = (f32x2){pp.y, pp.y}, p2 = (f32x2){pp.z, pp.z}, p3 = (f32x2){pp.w, pp.w};
;                     const unsigned wds[4] = {vv[e].x, vv[e].y, vv[e].z, vv[e].w};
; #pragma unroll
;                     for (int w = 0; w < 4; ++w) {
;                         const f32x2 lo = __builtin_amdgcn_cvt_pk_f32_fp8((int)wds[w], false), hi = __builtin_amdgcn_cvt_pk_f32_fp8((int)wds[w], true);
;                         oa2[0][2 * w] = __builtin_elementwise_fma(lo, p0, oa2[0][2 * w]); oa2[0][2 * w + 1] = __builtin_elementwise_fma(hi, p0, oa2[0][2 * w + 1]);
;                         oa2[1][2 * w] = __builtin_elementwise_fma(lo, p1, oa2[1][2 * w]); oa2[1][2 * w + 1] = __builtin_elementwise_fma(hi, p1, oa2[1][2 * w + 1]);
;                         oa2[2][2 * w] = __builtin_elementwise_fma(lo, p2, oa2[2][2 * w]); oa2[2][2 * w + 1] = __builtin_elementwise_fma(hi, p2, oa2[2][2 * w + 1]);
;                         oa2[3][2 * w] = __builtin_elementwise_fma(lo, p3, oa2[3][2 * w]); oa2[3][2 * w + 1] = __builtin_elementwise_fma(hi, p3, oa2[3][2 * w + 1]); }
	v_cvt_pk_f32_fp8_e32 v[30:31], v32
	v_cvt_pk_f32_fp8_sdwa v[44:45], v32 src0_sel:WORD_1
	s_waitcnt lgkmcnt(0)
	v_mov_b32_e32 v126, v39
	v_pk_fma_f32 v[76:77], v[30:31], v[36:37], v[84:85] op_sel_hi:[1,0,1]
	v_pk_fma_f32 v[80:81], v[30:31], v[36:37], v[88:89] op_sel:[0,1,0]
	v_pk_fma_f32 v[84:85], v[30:31], v[38:39], v[92:93] op_sel_hi:[1,0,1]
	v_pk_fma_f32 v[88:89], v[30:31], v[126:127], v[96:97] op_sel_hi:[1,0,1]
	v_cvt_pk_f32_fp8_e32 v[30:31], v33
	v_cvt_pk_f32_fp8_sdwa v[32:33], v33 src0_sel:WORD_1
	v_pk_fma_f32 v[78:79], v[44:45], v[36:37], v[86:87] op_sel_hi:[1,0,1]
	v_pk_fma_f32 v[86:87], v[44:45], v[38:39], v[94:95] op_sel_hi:[1,0,1]
	v_pk_fma_f32 v[60:61], v[30:31], v[36:37], v[68:69] op_sel_hi:[1,0,1]
	v_pk_fma_f32 v[64:65], v[30:31], v[36:37], v[72:73] op_sel:[0,1,0]
	v_pk_fma_f32 v[66:67], v[32:33], v[36:37], v[74:75] op_sel:[0,1,0]
	v_pk_fma_f32 v[68:69], v[30:31], v[38:39], v[108:109] op_sel_hi:[1,0,1]
	v_pk_fma_f32 v[72:73], v[30:31], v[126:127], v[106:107] op_sel_hi:[1,0,1]
	v_pk_fma_f32 v[74:75], v[32:33], v[126:127], v[28:29] op_sel_hi:[1,0,1]
	v_cvt_pk_f32_fp8_e32 v[28:29], v34
	v_cvt_pk_f32_fp8_sdwa v[30:31], v34 src0_sel:WORD_1
	v_cvt_pk_f32_fp8_e32 v[92:93], v35
	v_cvt_pk_f32_fp8_sdwa v[94:95], v35 src0_sel:WORD_1
	v_pk_fma_f32 v[82:83], v[44:45], v[36:37], v[90:91] op_sel:[0,1,0]
	v_pk_fma_f32 v[90:91], v[44:45], v[126:127], v[98:99] op_sel_hi:[1,0,1]
	v_pk_fma_f32 v[62:63], v[32:33], v[36:37], v[70:71] op_sel_hi:[1,0,1]
	v_pk_fma_f32 v[70:71], v[32:33], v[38:39], v[110:111] op_sel_hi:[1,0,1]
	v_pk_fma_f32 v[44:45], v[28:29], v[36:37], v[52:53] op_sel_hi:[1,0,1]
	v_pk_fma_f32 v[46:47], v[30:31], v[36:37], v[54:55] op_sel_hi:[1,0,1]
	v_pk_fma_f32 v[48:49], v[28:29], v[36:37], v[56:57] op_sel:[0,1,0]
	v_pk_fma_f32 v[50:51], v[30:31], v[36:37], v[58:59] op_sel:[0,1,0]
	v_pk_fma_f32 v[52:53], v[28:29], v[38:39], v[112:113] op_sel_hi:[1,0,1]
	v_pk_fma_f32 v[54:55], v[30:31], v[38:39], v[114:115] op_sel_hi:[1,0,1]
	v_pk_fma_f32 v[56:57], v[28:29], v[126:127], v[116:117] op_sel_hi:[1,0,1]
	v_pk_fma_f32 v[58:59], v[30:31], v[126:127], v[118:119] op_sel_hi:[1,0,1]
	v_pk_fma_f32 v[28:29], v[92:93], v[36:37], v[120:121] op_sel_hi:[1,0,1]
	v_pk_fma_f32 v[30:31], v[94:95], v[36:37], v[122:123] op_sel_hi:[1,0,1]
	v_pk_fma_f32 v[32:33], v[92:93], v[36:37], v[40:41] op_sel:[0,1,0]
	v_pk_fma_f32 v[34:35], v[94:95], v[36:37], v[42:43] op_sel:[0,1,0]
	v_pk_fma_f32 v[36:37], v[92:93], v[38:39], v[100:101] op_sel_hi:[1,0,1]
	v_pk_fma_f32 v[38:39], v[94:95], v[38:39], v[102:103] op_sel_hi:[1,0,1]
	v_pk_fma_f32 v[40:41], v[92:93], v[126:127], v[124:125] op_sel_hi:[1,0,1]
	v_pk_fma_f32 v[42:43], v[94:95], v[126:127], v[104:105] op_sel_hi:[1,0,1]
	ds_read_b128 v[92:95], v225 offset:1152
	s_waitcnt vmcnt(6)
	v_cvt_pk_f32_fp8_e32 v[98:99], v24
	v_cvt_pk_f32_fp8_sdwa v[100:101], v24 src0_sel:WORD_1
	s_waitcnt lgkmcnt(0)
	v_mov_b32_e32 v96, v95
	v_pk_fma_f32 v[76:77], v[98:99], v[92:93], v[76:77] op_sel_hi:[1,0,1]
	v_pk_fma_f32 v[80:81], v[98:99], v[92:93], v[80:81] op_sel:[0,1,0]
	v_pk_fma_f32 v[84:85], v[98:99], v[94:95], v[84:85] op_sel_hi:[1,0,1]
	v_pk_fma_f32 v[88:89], v[98:99], v[96:97], v[88:89] op_sel_hi:[1,0,1]
	v_cvt_pk_f32_fp8_e32 v[98:99], v25
	v_pk_fma_f32 v[78:79], v[100:101], v[92:93], v[78:79] op_sel_hi:[1,0,1]
	v_pk_fma_f32 v[82:83], v[100:101], v[92:93], v[82:83] op_sel:[0,1,0]
	v_pk_fma_f32 v[86:87], v[100:101], v[94:95], v[86:87] op_sel_hi:[1,0,1]
	v_pk_fma_f32 v[90:91], v[100:101], v[96:97], v[90:91] op_sel_hi:[1,0,1]
	v_cvt_pk_f32_fp8_sdwa v[24:25], v25 src0_sel:WORD_1
	v_pk_fma_f32 v[100:101], v[98:99], v[94:95], v[68:69] op_sel_hi:[1,0,1]
	v_cvt_pk_f32_fp8_e32 v[68:69], v26
	v_pk_fma_f32 v[60:61], v[98:99], v[92:93], v[60:61] op_sel_hi:[1,0,1]
	v_pk_fma_f32 v[102:103], v[24:25], v[94:95], v[70:71] op_sel_hi:[1,0,1]
	v_cvt_pk_f32_fp8_sdwa v[70:71], v26 src0_sel:WORD_1
	v_pk_fma_f32 v[104:105], v[68:69], v[94:95], v[52:53] op_sel_hi:[1,0,1]
	v_cvt_pk_f32_fp8_e32 v[52:53], v27
	v_cvt_pk_f32_fp8_sdwa v[26:27], v27 src0_sel:WORD_1
	v_pk_fma_f32 v[62:63], v[24:25], v[92:93], v[62:63] op_sel_hi:[1,0,1]
	v_pk_fma_f32 v[64:65], v[98:99], v[92:93], v[64:65] op_sel:[0,1,0]
	v_pk_fma_f32 v[112:113], v[52:53], v[92:93], v[28:29] op_sel_hi:[1,0,1]
	v_pk_fma_f32 v[114:115], v[26:27], v[92:93], v[30:31] op_sel_hi:[1,0,1]
	ds_read_b128 v[28:31], v225 offset:1280
	v_pk_fma_f32 v[66:67], v[24:25], v[92:93], v[66:67] op_sel:[0,1,0]
	v_pk_fma_f32 v[98:99], v[98:99], v[96:97], v[72:73] op_sel_hi:[1,0,1]
	v_pk_fma_f32 v[24:25], v[24:25], v[96:97], v[74:75] op_sel_hi:[1,0,1]
	v_pk_fma_f32 v[44:45], v[68:69], v[92:93], v[44:45] op_sel_hi:[1,0,1]
	v_pk_fma_f32 v[46:47], v[70:71], v[92:93], v[46:47] op_sel_hi:[1,0,1]
	v_pk_fma_f32 v[48:49], v[68:69], v[92:93], v[48:49] op_sel:[0,1,0]
	v_pk_fma_f32 v[50:51], v[70:71], v[92:93], v[50:51] op_sel:[0,1,0]
	v_pk_fma_f32 v[106:107], v[70:71], v[94:95], v[54:55] op_sel_hi:[1,0,1]
	v_pk_fma_f32 v[108:109], v[68:69], v[96:97], v[56:57] op_sel_hi:[1,0,1]
	v_pk_fma_f32 v[110:111], v[70:71], v[96:97], v[58:59] op_sel_hi:[1,0,1]
	v_pk_fma_f32 v[32:33], v[52:53], v[92:93], v[32:33] op_sel:[0,1,0]
	v_pk_fma_f32 v[34:35], v[26:27], v[92:93], v[34:35] op_sel:[0,1,0]
	v_pk_fma_f32 v[92:93], v[52:53], v[94:95], v[36:37] op_sel_hi:[1,0,1]
	v_pk_fma_f32 v[94:95], v[26:27], v[94:95], v[38:39] op_sel_hi:[1,0,1]
	v_pk_fma_f32 v[116:117], v[52:53], v[96:97], v[40:41] op_sel_hi:[1,0,1]
	v_pk_fma_f32 v[96:97], v[26:27], v[96:97], v[42:43] op_sel_hi:[1,0,1]
	s_waitcnt vmcnt(5)
	v_cvt_pk_f32_fp8_e32 v[26:27], v20
	s_waitcnt lgkmcnt(0)
; __device__ __forceinline__ void dsa_attend(const h16* PROJ, const unsigned short* IDX, const int* CNT, h16* MIXA, unsigned char* shm, unsigned* bar, unsigned xcc, unsigned xrank) {
;     ...
;             for (int s0 = 0; s0 < nsel; s0 += 128) {
;     ...
;                 for (int e = 0; e < 16; ++e) { const int slot = s0 + 8 * e + r8;
;                     if ((e & 3) == 0) __builtin_amdgcn_sched_barrier(0);
;                     const f32x4 pp = *(const f32x4*)(Pl + ((size_t)wid * 256 + slot) * 4);
;                     const f32x2 p0 = (f32x2){pp.x, pp.x}, p1 = (f32x2){pp.y, pp.y}, p2 = (f32x2){pp.z, pp.z}, p3 = (f32x2){pp.w, pp.w};
;                     const unsigned wds[4] = {vv[e].x, vv[e].y, vv[e].z, vv[e].w};
; #pragma unroll
;                     for (int w = 0; w < 4; ++w) {
;                         const f32x2 lo = __builtin_amdgcn_cvt_pk_f32_fp8((int)wds[w], false), hi = __builtin_amdgcn_cvt_pk_f32_fp8((int)wds[w], true);
;                         oa2[0][2 * w] = __builtin_elementwise_fma(lo, p0, oa2[0][2 * w]); oa2[0][2 * w + 1] = __builtin_elementwise_fma(hi, p0, oa2[0][2 * w + 1]);
;                         oa2[1][2 * w] = __builtin_elementwise_fma(lo, p1, oa2[1][2 * w]); oa2[1][2 * w + 1] = __builtin_elementwise_fma(hi, p1, oa2[1][2 * w + 1]);
;                         oa2[2][2 * w] = __builtin_elementwise_fma(lo, p2, oa2[2][2 * w]); oa2[2][2 * w + 1] = __builtin_elementwise_fma(hi, p2, oa2[2][2 * w + 1]);
;                         oa2[3][2 * w] = __builtin_elementwise_fma(lo, p3, oa2[3][2 * w]); oa2[3][2 * w + 1] = __builtin_elementwise_fma(hi, p3, oa2[3][2 * w + 1]); }
	v_mov_b32_e32 v118, v31
	v_cvt_pk_f32_fp8_sdwa v[36:37], v20 src0_sel:WORD_1
	v_pk_fma_f32 v[68:69], v[26:27], v[28:29], v[76:77] op_sel_hi:[1,0,1]
	v_pk_fma_f32 v[72:73], v[26:27], v[28:29], v[80:81] op_sel:[0,1,0]
	v_pk_fma_f32 v[76:77], v[26:27], v[30:31], v[84:85] op_sel_hi:[1,0,1]
	v_pk_fma_f32 v[80:81], v[26:27], v[118:119], v[88:89] op_sel_hi:[1,0,1]
	v_cvt_pk_f32_fp8_e32 v[26:27], v21
	v_cvt_pk_f32_fp8_sdwa v[20:21], v21 src0_sel:WORD_1
	v_pk_fma_f32 v[70:71], v[36:37], v[28:29], v[78:79] op_sel_hi:[1,0,1]
	v_pk_fma_f32 v[78:79], v[36:37], v[30:31], v[86:87] op_sel_hi:[1,0,1]
	v_cvt_pk_f32_fp8_e32 v[84:85], v23
	v_pk_fma_f32 v[54:55], v[20:21], v[28:29], v[62:63] op_sel_hi:[1,0,1]
	v_pk_fma_f32 v[58:59], v[20:21], v[28:29], v[66:67] op_sel:[0,1,0]
	v_pk_fma_f32 v[62:63], v[20:21], v[30:31], v[102:103] op_sel_hi:[1,0,1]
	v_pk_fma_f32 v[66:67], v[20:21], v[118:119], v[24:25] op_sel_hi:[1,0,1]
	v_cvt_pk_f32_fp8_e32 v[20:21], v22
	v_cvt_pk_f32_fp8_sdwa v[24:25], v22 src0_sel:WORD_1
	v_cvt_pk_f32_fp8_sdwa v[86:87], v23 src0_sel:WORD_1
	v_pk_fma_f32 v[74:75], v[36:37], v[28:29], v[82:83] op_sel:[0,1,0]
	v_pk_fma_f32 v[82:83], v[36:37], v[118:119], v[90:91] op_sel_hi:[1,0,1]
	v_pk_fma_f32 v[52:53], v[26:27], v[28:29], v[60:61] op_sel_hi:[1,0,1]
	v_pk_fma_f32 v[56:57], v[26:27], v[28:29], v[64:65] op_sel:[0,1,0]
	v_pk_fma_f32 v[60:61], v[26:27], v[30:31], v[100:101] op_sel_hi:[1,0,1]
	v_pk_fma_f32 v[64:65], v[26:27], v[118:119], v[98:99] op_sel_hi:[1,0,1]
	v_pk_fma_f32 v[36:37], v[20:21], v[28:29], v[44:45] op_sel_hi:[1,0,1]
	v_pk_fma_f32 v[38:39], v[24:25], v[28:29], v[46:47] op_sel_hi:[1,0,1]
	v_pk_fma_f32 v[40:41], v[20:21], v[28:29], v[48:49] op_sel:[0,1,0]
	v_pk_fma_f32 v[42:43], v[24:25], v[28:29], v[50:51] op_sel:[0,1,0]
	v_pk_fma_f32 v[44:45], v[20:21], v[30:31], v[104:105] op_sel_hi:[1,0,1]
	v_pk_fma_f32 v[46:47], v[24:25], v[30:31], v[106:107] op_sel_hi:[1,0,1]
	v_pk_fma_f32 v[48:49], v[20:21], v[118:119], v[108:109] op_sel_hi:[1,0,1]
	v_pk_fma_f32 v[50:51], v[24:25], v[118:119], v[110:111] op_sel_hi:[1,0,1]
	v_pk_fma_f32 v[20:21], v[84:85], v[28:29], v[112:113] op_sel_hi:[1,0,1]
	v_pk_fma_f32 v[22:23], v[86:87], v[28:29], v[114:115] op_sel_hi:[1,0,1]
	v_pk_fma_f32 v[24:25], v[84:85], v[28:29], v[32:33] op_sel:[0,1,0]
	v_pk_fma_f32 v[26:27], v[86:87], v[28:29], v[34:35] op_sel:[0,1,0]
	v_pk_fma_f32 v[28:29], v[84:85], v[30:31], v[92:93] op_sel_hi:[1,0,1]
	v_pk_fma_f32 v[30:31], v[86:87], v[30:31], v[94:95] op_sel_hi:[1,0,1]
	v_pk_fma_f32 v[32:33], v[84:85], v[118:119], v[116:117] op_sel_hi:[1,0,1]
	v_pk_fma_f32 v[34:35], v[86:87], v[118:119], v[96:97] op_sel_hi:[1,0,1]
	ds_read_b128 v[84:87], v225 offset:1408
	s_waitcnt vmcnt(4)
	v_cvt_pk_f32_fp8_e32 v[90:91], v16
	v_cvt_pk_f32_fp8_sdwa v[92:93], v16 src0_sel:WORD_1
	s_waitcnt lgkmcnt(0)
	v_mov_b32_e32 v88, v87
	v_pk_fma_f32 v[68:69], v[90:91], v[84:85], v[68:69] op_sel_hi:[1,0,1]
	v_pk_fma_f32 v[72:73], v[90:91], v[84:85], v[72:73] op_sel:[0,1,0]
	v_pk_fma_f32 v[76:77], v[90:91], v[86:87], v[76:77] op_sel_hi:[1,0,1]
	v_pk_fma_f32 v[80:81], v[90:91], v[88:89], v[80:81] op_sel_hi:[1,0,1]
	v_cvt_pk_f32_fp8_e32 v[90:91], v17
	v_cvt_pk_f32_fp8_sdwa v[16:17], v17 src0_sel:WORD_1
	v_pk_fma_f32 v[70:71], v[92:93], v[84:85], v[70:71] op_sel_hi:[1,0,1]
	v_pk_fma_f32 v[74:75], v[92:93], v[84:85], v[74:75] op_sel:[0,1,0]
	v_pk_fma_f32 v[52:53], v[90:91], v[84:85], v[52:53] op_sel_hi:[1,0,1]
	v_pk_fma_f32 v[54:55], v[16:17], v[84:85], v[54:55] op_sel_hi:[1,0,1]
	v_pk_fma_f32 v[58:59], v[16:17], v[84:85], v[58:59] op_sel:[0,1,0]
	v_pk_fma_f32 v[62:63], v[16:17], v[86:87], v[62:63] op_sel_hi:[1,0,1]
	v_pk_fma_f32 v[66:67], v[16:17], v[88:89], v[66:67] op_sel_hi:[1,0,1]
	v_cvt_pk_f32_fp8_e32 v[16:17], v18
	v_pk_fma_f32 v[56:57], v[90:91], v[84:85], v[56:57] op_sel:[0,1,0]
	v_pk_fma_f32 v[60:61], v[90:91], v[86:87], v[60:61] op_sel_hi:[1,0,1]
	v_pk_fma_f32 v[64:65], v[90:91], v[88:89], v[64:65] op_sel_hi:[1,0,1]
	v_cvt_pk_f32_fp8_sdwa v[90:91], v18 src0_sel:WORD_1
	v_pk_fma_f32 v[36:37], v[16:17], v[84:85], v[36:37] op_sel_hi:[1,0,1]
	v_pk_fma_f32 v[40:41], v[16:17], v[84:85], v[40:41] op_sel:[0,1,0]
	v_pk_fma_f32 v[44:45], v[16:17], v[86:87], v[44:45] op_sel_hi:[1,0,1]
	v_pk_fma_f32 v[48:49], v[16:17], v[88:89], v[48:49] op_sel_hi:[1,0,1]
	v_cvt_pk_f32_fp8_e32 v[16:17], v19
	v_cvt_pk_f32_fp8_sdwa v[18:19], v19 src0_sel:WORD_1
	v_pk_fma_f32 v[78:79], v[92:93], v[86:87], v[78:79] op_sel_hi:[1,0,1]
	v_pk_fma_f32 v[82:83], v[92:93], v[88:89], v[82:83] op_sel_hi:[1,0,1]
	v_pk_fma_f32 v[38:39], v[90:91], v[84:85], v[38:39] op_sel_hi:[1,0,1]
	v_pk_fma_f32 v[42:43], v[90:91], v[84:85], v[42:43] op_sel:[0,1,0]
	v_pk_fma_f32 v[46:47], v[90:91], v[86:87], v[46:47] op_sel_hi:[1,0,1]
	v_pk_fma_f32 v[50:51], v[90:91], v[88:89], v[50:51] op_sel_hi:[1,0,1]
	v_pk_fma_f32 v[20:21], v[16:17], v[84:85], v[20:21] op_sel_hi:[1,0,1]
	v_pk_fma_f32 v[22:23], v[18:19], v[84:85], v[22:23] op_sel_hi:[1,0,1]
	v_pk_fma_f32 v[24:25], v[16:17], v[84:85], v[24:25] op_sel:[0,1,0]
	v_pk_fma_f32 v[26:27], v[18:19], v[84:85], v[26:27] op_sel:[0,1,0]
	v_pk_fma_f32 v[28:29], v[16:17], v[86:87], v[28:29] op_sel_hi:[1,0,1]
	v_pk_fma_f32 v[30:31], v[18:19], v[86:87], v[30:31] op_sel_hi:[1,0,1]
	v_pk_fma_f32 v[32:33], v[16:17], v[88:89], v[32:33] op_sel_hi:[1,0,1]
	v_pk_fma_f32 v[34:35], v[18:19], v[88:89], v[34:35] op_sel_hi:[1,0,1]
	ds_read_b128 v[16:19], v225 offset:1536
	s_waitcnt vmcnt(3)
	v_cvt_pk_f32_fp8_e32 v[86:87], v12
	v_cvt_pk_f32_fp8_sdwa v[88:89], v12 src0_sel:WORD_1
	s_addk_i32 s50, 0x80
	s_cmp_ge_u32 s50, s67
	s_waitcnt lgkmcnt(0)
; __device__ __forceinline__ void dsa_attend(const h16* PROJ, const unsigned short* IDX, const int* CNT, h16* MIXA, unsigned char* shm, unsigned* bar, unsigned xcc, unsigned xrank) {
;     ...
;                 for (int e = 0; e < 16; ++e) { const int slot = s0 + 8 * e + r8;
;                     if ((e & 3) == 0) __builtin_amdgcn_sched_barrier(0);
;                     const f32x4 pp = *(const f32x4*)(Pl + ((size_t)wid * 256 + slot) * 4);
;                     const f32x2 p0 = (f32x2){pp.x, pp.x}, p1 = (f32x2){pp.y, pp.y}, p2 = (f32x2){pp.z, pp.z}, p3 = (f32x2){pp.w, pp.w};
;                     const unsigned wds[4] = {vv[e].x, vv[e].y, vv[e].z, vv[e].w};
; #pragma unroll
;                     for (int w = 0; w < 4; ++w) {
;                         const f32x2 lo = __builtin_amdgcn_cvt_pk_f32_fp8((int)wds[w], false), hi = __builtin_amdgcn_cvt_pk_f32_fp8((int)wds[w], true);
;                         oa2[0][2 * w] = __builtin_elementwise_fma(lo, p0, oa2[0][2 * w]); oa2[0][2 * w + 1] = __builtin_elementwise_fma(hi, p0, oa2[0][2 * w + 1]);
;                         oa2[1][2 * w] = __builtin_elementwise_fma(lo, p1, oa2[1][2 * w]); oa2[1][2 * w + 1] = __builtin_elementwise_fma(hi, p1, oa2[1][2 * w + 1]);
;                         oa2[2][2 * w] = __builtin_elementwise_fma(lo, p2, oa2[2][2 * w]); oa2[2][2 * w + 1] = __builtin_elementwise_fma(hi, p2, oa2[2][2 * w + 1]);
;                         oa2[3][2 * w] = __builtin_elementwise_fma(lo, p3, oa2[3][2 * w]); oa2[3][2 * w + 1] = __builtin_elementwise_fma(hi, p3, oa2[3][2 * w + 1]); }
	v_mov_b32_e32 v84, v19
	v_pk_fma_f32 v[68:69], v[86:87], v[16:17], v[68:69] op_sel_hi:[1,0,1]
	v_pk_fma_f32 v[72:73], v[86:87], v[16:17], v[72:73] op_sel:[0,1,0]
	v_pk_fma_f32 v[76:77], v[86:87], v[18:19], v[76:77] op_sel_hi:[1,0,1]
	v_pk_fma_f32 v[80:81], v[86:87], v[84:85], v[80:81] op_sel_hi:[1,0,1]
	v_cvt_pk_f32_fp8_e32 v[86:87], v13
	v_cvt_pk_f32_fp8_sdwa v[12:13], v13 src0_sel:WORD_1
	v_pk_fma_f32 v[70:71], v[88:89], v[16:17], v[70:71] op_sel_hi:[1,0,1]
	v_pk_fma_f32 v[74:75], v[88:89], v[16:17], v[74:75] op_sel:[0,1,0]
	v_pk_fma_f32 v[52:53], v[86:87], v[16:17], v[52:53] op_sel_hi:[1,0,1]
	v_pk_fma_f32 v[54:55], v[12:13], v[16:17], v[54:55] op_sel_hi:[1,0,1]
	v_pk_fma_f32 v[58:59], v[12:13], v[16:17], v[58:59] op_sel:[0,1,0]
	v_pk_fma_f32 v[62:63], v[12:13], v[18:19], v[62:63] op_sel_hi:[1,0,1]
	v_pk_fma_f32 v[66:67], v[12:13], v[84:85], v[66:67] op_sel_hi:[1,0,1]
	v_cvt_pk_f32_fp8_e32 v[12:13], v14
	v_pk_fma_f32 v[56:57], v[86:87], v[16:17], v[56:57] op_sel:[0,1,0]
	v_pk_fma_f32 v[60:61], v[86:87], v[18:19], v[60:61] op_sel_hi:[1,0,1]
	v_pk_fma_f32 v[64:65], v[86:87], v[84:85], v[64:65] op_sel_hi:[1,0,1]
	v_cvt_pk_f32_fp8_sdwa v[86:87], v14 src0_sel:WORD_1
	v_pk_fma_f32 v[36:37], v[12:13], v[16:17], v[36:37] op_sel_hi:[1,0,1]
	v_pk_fma_f32 v[40:41], v[12:13], v[16:17], v[40:41] op_sel:[0,1,0]
	v_pk_fma_f32 v[44:45], v[12:13], v[18:19], v[44:45] op_sel_hi:[1,0,1]
	v_pk_fma_f32 v[48:49], v[12:13], v[84:85], v[48:49] op_sel_hi:[1,0,1]
	v_cvt_pk_f32_fp8_e32 v[12:13], v15
	v_cvt_pk_f32_fp8_sdwa v[14:15], v15 src0_sel:WORD_1
	v_pk_fma_f32 v[78:79], v[88:89], v[18:19], v[78:79] op_sel_hi:[1,0,1]
	v_pk_fma_f32 v[38:39], v[86:87], v[16:17], v[38:39] op_sel_hi:[1,0,1]
	v_pk_fma_f32 v[42:43], v[86:87], v[16:17], v[42:43] op_sel:[0,1,0]
	v_pk_fma_f32 v[46:47], v[86:87], v[18:19], v[46:47] op_sel_hi:[1,0,1]
	v_pk_fma_f32 v[20:21], v[12:13], v[16:17], v[20:21] op_sel_hi:[1,0,1]
	v_pk_fma_f32 v[22:23], v[14:15], v[16:17], v[22:23] op_sel_hi:[1,0,1]
	v_pk_fma_f32 v[24:25], v[12:13], v[16:17], v[24:25] op_sel:[0,1,0]
	v_pk_fma_f32 v[16:17], v[14:15], v[16:17], v[26:27] op_sel:[0,1,0]
	v_pk_fma_f32 v[26:27], v[12:13], v[18:19], v[28:29] op_sel_hi:[1,0,1]
	v_pk_fma_f32 v[18:19], v[14:15], v[18:19], v[30:31] op_sel_hi:[1,0,1]
	v_pk_fma_f32 v[28:29], v[12:13], v[84:85], v[32:33] op_sel_hi:[1,0,1]
	v_pk_fma_f32 v[30:31], v[14:15], v[84:85], v[34:35] op_sel_hi:[1,0,1]
	ds_read_b128 v[12:15], v225 offset:1664
	v_pk_fma_f32 v[82:83], v[88:89], v[84:85], v[82:83] op_sel_hi:[1,0,1]
	v_pk_fma_f32 v[50:51], v[86:87], v[84:85], v[50:51] op_sel_hi:[1,0,1]
	s_waitcnt vmcnt(2)
	v_cvt_pk_f32_fp8_e32 v[34:35], v8
	v_cvt_pk_f32_fp8_sdwa v[84:85], v8 src0_sel:WORD_1
	s_waitcnt lgkmcnt(0)
	v_mov_b32_e32 v32, v15
	v_pk_fma_f32 v[68:69], v[34:35], v[12:13], v[68:69] op_sel_hi:[1,0,1]
	v_pk_fma_f32 v[72:73], v[34:35], v[12:13], v[72:73] op_sel:[0,1,0]
	v_pk_fma_f32 v[76:77], v[34:35], v[14:15], v[76:77] op_sel_hi:[1,0,1]
	v_pk_fma_f32 v[34:35], v[34:35], v[32:33], v[80:81] op_sel_hi:[1,0,1]
	v_pk_fma_f32 v[80:81], v[84:85], v[32:33], v[82:83] op_sel_hi:[1,0,1]
	v_cvt_pk_f32_fp8_e32 v[82:83], v9
	v_cvt_pk_f32_fp8_sdwa v[8:9], v9 src0_sel:WORD_1
	v_pk_fma_f32 v[70:71], v[84:85], v[12:13], v[70:71] op_sel_hi:[1,0,1]
	v_pk_fma_f32 v[74:75], v[84:85], v[12:13], v[74:75] op_sel:[0,1,0]
	v_pk_fma_f32 v[52:53], v[82:83], v[12:13], v[52:53] op_sel_hi:[1,0,1]
	v_pk_fma_f32 v[54:55], v[8:9], v[12:13], v[54:55] op_sel_hi:[1,0,1]
	v_pk_fma_f32 v[58:59], v[8:9], v[12:13], v[58:59] op_sel:[0,1,0]
	v_pk_fma_f32 v[62:63], v[8:9], v[14:15], v[62:63] op_sel_hi:[1,0,1]
	v_pk_fma_f32 v[66:67], v[8:9], v[32:33], v[66:67] op_sel_hi:[1,0,1]
	v_cvt_pk_f32_fp8_e32 v[8:9], v10
	v_pk_fma_f32 v[56:57], v[82:83], v[12:13], v[56:57] op_sel:[0,1,0]
	v_pk_fma_f32 v[60:61], v[82:83], v[14:15], v[60:61] op_sel_hi:[1,0,1]
	v_pk_fma_f32 v[64:65], v[82:83], v[32:33], v[64:65] op_sel_hi:[1,0,1]
	v_cvt_pk_f32_fp8_sdwa v[82:83], v10 src0_sel:WORD_1
	v_pk_fma_f32 v[36:37], v[8:9], v[12:13], v[36:37] op_sel_hi:[1,0,1]
	v_pk_fma_f32 v[40:41], v[8:9], v[12:13], v[40:41] op_sel:[0,1,0]
	v_pk_fma_f32 v[44:45], v[8:9], v[14:15], v[44:45] op_sel_hi:[1,0,1]
	v_pk_fma_f32 v[48:49], v[8:9], v[32:33], v[48:49] op_sel_hi:[1,0,1]
	v_cvt_pk_f32_fp8_e32 v[8:9], v11
	v_cvt_pk_f32_fp8_sdwa v[10:11], v11 src0_sel:WORD_1
	v_pk_fma_f32 v[78:79], v[84:85], v[14:15], v[78:79] op_sel_hi:[1,0,1]
	v_pk_fma_f32 v[38:39], v[82:83], v[12:13], v[38:39] op_sel_hi:[1,0,1]
	v_pk_fma_f32 v[42:43], v[82:83], v[12:13], v[42:43] op_sel:[0,1,0]
	v_pk_fma_f32 v[46:47], v[82:83], v[14:15], v[46:47] op_sel_hi:[1,0,1]
	v_pk_fma_f32 v[20:21], v[8:9], v[12:13], v[20:21] op_sel_hi:[1,0,1]
	v_pk_fma_f32 v[22:23], v[10:11], v[12:13], v[22:23] op_sel_hi:[1,0,1]
	v_pk_fma_f32 v[24:25], v[8:9], v[12:13], v[24:25] op_sel:[0,1,0]
	v_pk_fma_f32 v[12:13], v[10:11], v[12:13], v[16:17] op_sel:[0,1,0]
	v_pk_fma_f32 v[16:17], v[8:9], v[14:15], v[26:27] op_sel_hi:[1,0,1]
	v_pk_fma_f32 v[14:15], v[10:11], v[14:15], v[18:19] op_sel_hi:[1,0,1]
	v_pk_fma_f32 v[18:19], v[8:9], v[32:33], v[28:29] op_sel_hi:[1,0,1]
	v_pk_fma_f32 v[26:27], v[10:11], v[32:33], v[30:31] op_sel_hi:[1,0,1]
	ds_read_b128 v[8:11], v225 offset:1792
	s_waitcnt vmcnt(1)
	v_cvt_pk_f32_fp8_e32 v[30:31], v4
	v_pk_fma_f32 v[50:51], v[82:83], v[32:33], v[50:51] op_sel_hi:[1,0,1]
	v_cvt_pk_f32_fp8_sdwa v[32:33], v4 src0_sel:WORD_1
	s_waitcnt lgkmcnt(0)
; __device__ __forceinline__ void dsa_attend(const h16* PROJ, const unsigned short* IDX, const int* CNT, h16* MIXA, unsigned char* shm, unsigned* bar, unsigned xcc, unsigned xrank) {
;     ...
;             for (int s0 = 0; s0 < nsel; s0 += 128) {
;     ...
;                 for (int e = 0; e < 16; ++e) { const int slot = s0 + 8 * e + r8;
;                     if ((e & 3) == 0) __builtin_amdgcn_sched_barrier(0);
;                     const f32x4 pp = *(const f32x4*)(Pl + ((size_t)wid * 256 + slot) * 4);
;                     const f32x2 p0 = (f32x2){pp.x, pp.x}, p1 = (f32x2){pp.y, pp.y}, p2 = (f32x2){pp.z, pp.z}, p3 = (f32x2){pp.w, pp.w};
;                     const unsigned wds[4] = {vv[e].x, vv[e].y, vv[e].z, vv[e].w};
; #pragma unroll
;                     for (int w = 0; w < 4; ++w) {
;                         const f32x2 lo = __builtin_amdgcn_cvt_pk_f32_fp8((int)wds[w], false), hi = __builtin_amdgcn_cvt_pk_f32_fp8((int)wds[w], true);
;                         oa2[0][2 * w] = __builtin_elementwise_fma(lo, p0, oa2[0][2 * w]); oa2[0][2 * w + 1] = __builtin_elementwise_fma(hi, p0, oa2[0][2 * w + 1]);
;                         oa2[1][2 * w] = __builtin_elementwise_fma(lo, p1, oa2[1][2 * w]); oa2[1][2 * w + 1] = __builtin_elementwise_fma(hi, p1, oa2[1][2 * w + 1]);
;                         oa2[2][2 * w] = __builtin_elementwise_fma(lo, p2, oa2[2][2 * w]); oa2[2][2 * w + 1] = __builtin_elementwise_fma(hi, p2, oa2[2][2 * w + 1]);
;                         oa2[3][2 * w] = __builtin_elementwise_fma(lo, p3, oa2[3][2 * w]); oa2[3][2 * w + 1] = __builtin_elementwise_fma(hi, p3, oa2[3][2 * w + 1]); }
	v_mov_b32_e32 v28, v11
	v_pk_fma_f32 v[68:69], v[30:31], v[8:9], v[68:69] op_sel_hi:[1,0,1]
	v_pk_fma_f32 v[72:73], v[30:31], v[8:9], v[72:73] op_sel:[0,1,0]
	v_pk_fma_f32 v[76:77], v[30:31], v[10:11], v[76:77] op_sel_hi:[1,0,1]
	v_pk_fma_f32 v[30:31], v[30:31], v[28:29], v[34:35] op_sel_hi:[1,0,1]
	v_cvt_pk_f32_fp8_e32 v[34:35], v5
	v_cvt_pk_f32_fp8_sdwa v[4:5], v5 src0_sel:WORD_1
	v_pk_fma_f32 v[70:71], v[32:33], v[8:9], v[70:71] op_sel_hi:[1,0,1]
	v_pk_fma_f32 v[74:75], v[32:33], v[8:9], v[74:75] op_sel:[0,1,0]
	v_pk_fma_f32 v[78:79], v[32:33], v[10:11], v[78:79] op_sel_hi:[1,0,1]
	v_pk_fma_f32 v[32:33], v[32:33], v[28:29], v[80:81] op_sel_hi:[1,0,1]
	v_pk_fma_f32 v[52:53], v[34:35], v[8:9], v[52:53] op_sel_hi:[1,0,1]
	v_pk_fma_f32 v[54:55], v[4:5], v[8:9], v[54:55] op_sel_hi:[1,0,1]
	v_pk_fma_f32 v[56:57], v[34:35], v[8:9], v[56:57] op_sel:[0,1,0]
	v_pk_fma_f32 v[58:59], v[4:5], v[8:9], v[58:59] op_sel:[0,1,0]
	v_pk_fma_f32 v[80:81], v[34:35], v[10:11], v[60:61] op_sel_hi:[1,0,1]
	v_pk_fma_f32 v[62:63], v[4:5], v[10:11], v[62:63] op_sel_hi:[1,0,1]
	v_pk_fma_f32 v[34:35], v[34:35], v[28:29], v[64:65] op_sel_hi:[1,0,1]
	v_pk_fma_f32 v[64:65], v[4:5], v[28:29], v[66:67] op_sel_hi:[1,0,1]
	v_cvt_pk_f32_fp8_e32 v[4:5], v6
	v_cvt_pk_f32_fp8_sdwa v[60:61], v6 src0_sel:WORD_1
	v_pk_fma_f32 v[36:37], v[4:5], v[8:9], v[36:37] op_sel_hi:[1,0,1]
	v_pk_fma_f32 v[40:41], v[4:5], v[8:9], v[40:41] op_sel:[0,1,0]
	v_pk_fma_f32 v[44:45], v[4:5], v[10:11], v[44:45] op_sel_hi:[1,0,1]
	v_pk_fma_f32 v[48:49], v[4:5], v[28:29], v[48:49] op_sel_hi:[1,0,1]
	v_cvt_pk_f32_fp8_e32 v[4:5], v7
	v_cvt_pk_f32_fp8_sdwa v[6:7], v7 src0_sel:WORD_1
	v_pk_fma_f32 v[38:39], v[60:61], v[8:9], v[38:39] op_sel_hi:[1,0,1]
	v_pk_fma_f32 v[42:43], v[60:61], v[8:9], v[42:43] op_sel:[0,1,0]
	v_pk_fma_f32 v[46:47], v[60:61], v[10:11], v[46:47] op_sel_hi:[1,0,1]
	v_pk_fma_f32 v[20:21], v[4:5], v[8:9], v[20:21] op_sel_hi:[1,0,1]
	v_pk_fma_f32 v[22:23], v[6:7], v[8:9], v[22:23] op_sel_hi:[1,0,1]
	v_pk_fma_f32 v[24:25], v[4:5], v[8:9], v[24:25] op_sel:[0,1,0]
	v_pk_fma_f32 v[8:9], v[6:7], v[8:9], v[12:13] op_sel:[0,1,0]
	v_pk_fma_f32 v[12:13], v[4:5], v[10:11], v[16:17] op_sel_hi:[1,0,1]
	v_pk_fma_f32 v[10:11], v[6:7], v[10:11], v[14:15] op_sel_hi:[1,0,1]
	v_pk_fma_f32 v[14:15], v[4:5], v[28:29], v[18:19] op_sel_hi:[1,0,1]
	v_pk_fma_f32 v[16:17], v[6:7], v[28:29], v[26:27] op_sel_hi:[1,0,1]
	ds_read_b128 v[4:7], v225 offset:1920
	s_waitcnt vmcnt(0)
	v_cvt_pk_f32_fp8_e32 v[26:27], v0
	v_pk_fma_f32 v[50:51], v[60:61], v[28:29], v[50:51] op_sel_hi:[1,0,1]
	v_cvt_pk_f32_fp8_sdwa v[28:29], v0 src0_sel:WORD_1
	v_add_u32_e32 v225, 0x800, v225
	s_waitcnt lgkmcnt(0)
	v_mov_b32_e32 v18, v7
	v_pk_fma_f32 v[110:111], v[26:27], v[4:5], v[68:69] op_sel_hi:[1,0,1]
	v_pk_fma_f32 v[104:105], v[26:27], v[4:5], v[72:73] op_sel:[0,1,0]
	v_pk_fma_f32 v[86:87], v[26:27], v[6:7], v[76:77] op_sel_hi:[1,0,1]
	v_pk_fma_f32 v[68:69], v[26:27], v[18:19], v[30:31] op_sel_hi:[1,0,1]
	v_cvt_pk_f32_fp8_e32 v[26:27], v1
	v_cvt_pk_f32_fp8_sdwa v[0:1], v1 src0_sel:WORD_1
	v_pk_fma_f32 v[76:77], v[28:29], v[6:7], v[78:79] op_sel_hi:[1,0,1]
	v_pk_fma_f32 v[92:93], v[28:29], v[4:5], v[74:75] op_sel:[0,1,0]
	v_pk_fma_f32 v[118:119], v[26:27], v[4:5], v[52:53] op_sel_hi:[1,0,1]
	v_pk_fma_f32 v[116:117], v[0:1], v[4:5], v[54:55] op_sel_hi:[1,0,1]
	v_pk_fma_f32 v[96:97], v[0:1], v[4:5], v[58:59] op_sel:[0,1,0]
	v_pk_fma_f32 v[78:79], v[0:1], v[6:7], v[62:63] op_sel_hi:[1,0,1]
	v_pk_fma_f32 v[62:63], v[0:1], v[18:19], v[64:65] op_sel_hi:[1,0,1]
	v_cvt_pk_f32_fp8_e32 v[0:1], v2
	v_pk_fma_f32 v[98:99], v[26:27], v[4:5], v[56:57] op_sel:[0,1,0]
	v_pk_fma_f32 v[90:91], v[26:27], v[6:7], v[80:81] op_sel_hi:[1,0,1]
	v_pk_fma_f32 v[72:73], v[26:27], v[18:19], v[34:35] op_sel_hi:[1,0,1]
	v_cvt_pk_f32_fp8_sdwa v[26:27], v2 src0_sel:WORD_1
	v_pk_fma_f32 v[120:121], v[0:1], v[4:5], v[36:37] op_sel_hi:[1,0,1]
	v_pk_fma_f32 v[102:103], v[0:1], v[4:5], v[40:41] op_sel:[0,1,0]
	v_pk_fma_f32 v[82:83], v[0:1], v[6:7], v[44:45] op_sel_hi:[1,0,1]
	v_pk_fma_f32 v[74:75], v[0:1], v[18:19], v[48:49] op_sel_hi:[1,0,1]
	v_cvt_pk_f32_fp8_e32 v[0:1], v3
	v_cvt_pk_f32_fp8_sdwa v[2:3], v3 src0_sel:WORD_1
	v_pk_fma_f32 v[112:113], v[28:29], v[4:5], v[70:71] op_sel_hi:[1,0,1]
	v_pk_fma_f32 v[60:61], v[28:29], v[18:19], v[32:33] op_sel_hi:[1,0,1]
	v_pk_fma_f32 v[108:109], v[26:27], v[4:5], v[38:39] op_sel_hi:[1,0,1]
	v_pk_fma_f32 v[100:101], v[26:27], v[4:5], v[42:43] op_sel:[0,1,0]
	v_pk_fma_f32 v[80:81], v[26:27], v[6:7], v[46:47] op_sel_hi:[1,0,1]
	v_pk_fma_f32 v[64:65], v[26:27], v[18:19], v[50:51] op_sel_hi:[1,0,1]
	v_pk_fma_f32 v[122:123], v[0:1], v[4:5], v[20:21] op_sel_hi:[1,0,1]
	v_pk_fma_f32 v[114:115], v[2:3], v[4:5], v[22:23] op_sel_hi:[1,0,1]
	v_pk_fma_f32 v[106:107], v[0:1], v[4:5], v[24:25] op_sel:[0,1,0]
	v_pk_fma_f32 v[94:95], v[2:3], v[4:5], v[8:9] op_sel:[0,1,0]
	v_pk_fma_f32 v[88:89], v[0:1], v[6:7], v[12:13] op_sel_hi:[1,0,1]
	v_pk_fma_f32 v[84:85], v[2:3], v[6:7], v[10:11] op_sel_hi:[1,0,1]
	v_pk_fma_f32 v[70:71], v[0:1], v[18:19], v[14:15] op_sel_hi:[1,0,1]
	v_pk_fma_f32 v[66:67], v[2:3], v[18:19], v[16:17] op_sel_hi:[1,0,1]
	s_cbranch_scc0 .LBB0_849
; __device__ __forceinline__ void dsa_attend(const h16* PROJ, const unsigned short* IDX, const int* CNT, h16* MIXA, unsigned char* shm, unsigned* bar, unsigned xcc, unsigned xrank) {
;     ...
; #pragma unroll
;             for (int h = 0; h < 4; ++h)
; #pragma unroll
;                 for (int d = 0; d < 8; ++d) { f32x2 v = oa2[h][d];
;                     v.x += __shfl_xor(v.x, 8); v.y += __shfl_xor(v.y, 8); v.x += __shfl_xor(v.x, 16); v.y += __shfl_xor(v.y, 16); v.x += __shfl_xor(v.x, 32); v.y += __shfl_xor(v.y, 32); oa2[h][d] = v; }
;             if (r8 == 0) {
;                 h16* orow = MIXA + (size_t)tokq * DM + (g * 4) * 128 + 16 * c8;
; #pragma unroll
;                 for (int h = 0; h < 4; ++h) { h16x8 w0, w1;
; #pragma unroll
;                     for (int d = 0; d < 4; ++d) { w0[2 * d] = (h16)oa2[h][d].x; w0[2 * d + 1] = (h16)oa2[h][d].y; w1[2 * d] = (h16)oa2[h][4 + d].x; w1[2 * d + 1] = (h16)oa2[h][4 + d].y; }
;                     *(h16x8*)(orow + h * 128) = w0; *(h16x8*)(orow + h * 128 + 8) = w1; }
;             }
	s_nop 1
	v_permlane32_swap_b32_e32 v110, v86
	v_permlane32_swap_b32_e32 v111, v87
	v_permlane32_swap_b32_e32 v112, v76
	v_permlane32_swap_b32_e32 v113, v77
	v_permlane32_swap_b32_e32 v118, v90
	v_permlane32_swap_b32_e32 v119, v91
	v_permlane32_swap_b32_e32 v116, v78
	v_permlane32_swap_b32_e32 v117, v79
	v_permlane32_swap_b32_e32 v120, v82
	v_permlane32_swap_b32_e32 v121, v83
	v_permlane32_swap_b32_e32 v108, v80
	v_permlane32_swap_b32_e32 v109, v81
	v_permlane32_swap_b32_e32 v122, v88
	v_permlane32_swap_b32_e32 v123, v89
	v_permlane32_swap_b32_e32 v114, v84
	v_permlane32_swap_b32_e32 v115, v85
	v_permlane32_swap_b32_e32 v104, v68
	v_permlane32_swap_b32_e32 v105, v69
	v_permlane32_swap_b32_e32 v92, v60
	v_permlane32_swap_b32_e32 v93, v61
	v_permlane32_swap_b32_e32 v98, v72
	v_permlane32_swap_b32_e32 v99, v73
	v_permlane32_swap_b32_e32 v96, v62
	v_permlane32_swap_b32_e32 v97, v63
	v_permlane32_swap_b32_e32 v102, v74
	v_permlane32_swap_b32_e32 v103, v75
	v_permlane32_swap_b32_e32 v100, v64
	v_permlane32_swap_b32_e32 v101, v65
	v_permlane32_swap_b32_e32 v106, v70
	v_permlane32_swap_b32_e32 v107, v71
	v_permlane32_swap_b32_e32 v94, v66
	v_permlane32_swap_b32_e32 v95, v67
	v_pk_add_f32 v[110:111], v[110:111], v[86:87]
	v_pk_add_f32 v[112:113], v[112:113], v[76:77]
	v_pk_add_f32 v[118:119], v[118:119], v[90:91]
	v_pk_add_f32 v[116:117], v[116:117], v[78:79]
	v_pk_add_f32 v[120:121], v[120:121], v[82:83]
	v_pk_add_f32 v[108:109], v[108:109], v[80:81]
	v_pk_add_f32 v[122:123], v[122:123], v[88:89]
	v_pk_add_f32 v[114:115], v[114:115], v[84:85]
	v_pk_add_f32 v[104:105], v[104:105], v[68:69]
	v_pk_add_f32 v[92:93], v[92:93], v[60:61]
	v_pk_add_f32 v[98:99], v[98:99], v[72:73]
	v_pk_add_f32 v[96:97], v[96:97], v[62:63]
	v_pk_add_f32 v[102:103], v[102:103], v[74:75]
	v_pk_add_f32 v[100:101], v[100:101], v[64:65]
	v_pk_add_f32 v[106:107], v[106:107], v[70:71]
	v_pk_add_f32 v[94:95], v[94:95], v[66:67]
	s_nop 1
	v_permlane16_swap_b32_e32 v110, v104
	v_permlane16_swap_b32_e32 v111, v105
	v_permlane16_swap_b32_e32 v112, v92
	v_permlane16_swap_b32_e32 v113, v93
	v_permlane16_swap_b32_e32 v118, v98
	v_permlane16_swap_b32_e32 v119, v99
	v_permlane16_swap_b32_e32 v116, v96
	v_permlane16_swap_b32_e32 v117, v97
	v_permlane16_swap_b32_e32 v120, v102
	v_permlane16_swap_b32_e32 v121, v103
	v_permlane16_swap_b32_e32 v108, v100
	v_permlane16_swap_b32_e32 v109, v101
	v_permlane16_swap_b32_e32 v122, v106
	v_permlane16_swap_b32_e32 v123, v107
	v_permlane16_swap_b32_e32 v114, v94
	v_permlane16_swap_b32_e32 v115, v95
	v_pk_add_f32 v[110:111], v[110:111], v[104:105]
	v_pk_add_f32 v[112:113], v[112:113], v[92:93]
	v_pk_add_f32 v[118:119], v[118:119], v[98:99]
	v_pk_add_f32 v[116:117], v[116:117], v[96:97]
	v_pk_add_f32 v[120:121], v[120:121], v[102:103]
	v_pk_add_f32 v[108:109], v[108:109], v[100:101]
	v_pk_add_f32 v[122:123], v[122:123], v[106:107]
	v_pk_add_f32 v[114:115], v[114:115], v[94:95]
	s_nop 1
	v_add_f32_dpp v110, v110, v110 row_ror:8 row_mask:0xf bank_mask:0xf
	v_add_f32_dpp v111, v111, v111 row_ror:8 row_mask:0xf bank_mask:0xf
	v_add_f32_dpp v112, v112, v112 row_ror:8 row_mask:0xf bank_mask:0xf
	v_add_f32_dpp v113, v113, v113 row_ror:8 row_mask:0xf bank_mask:0xf
	v_add_f32_dpp v118, v118, v118 row_ror:8 row_mask:0xf bank_mask:0xf
	v_add_f32_dpp v119, v119, v119 row_ror:8 row_mask:0xf bank_mask:0xf
	v_add_f32_dpp v116, v116, v116 row_ror:8 row_mask:0xf bank_mask:0xf
	v_add_f32_dpp v117, v117, v117 row_ror:8 row_mask:0xf bank_mask:0xf
	v_add_f32_dpp v120, v120, v120 row_ror:8 row_mask:0xf bank_mask:0xf
	v_add_f32_dpp v121, v121, v121 row_ror:8 row_mask:0xf bank_mask:0xf
	v_add_f32_dpp v108, v108, v108 row_ror:8 row_mask:0xf bank_mask:0xf
	v_add_f32_dpp v109, v109, v109 row_ror:8 row_mask:0xf bank_mask:0xf
	v_add_f32_dpp v122, v122, v122 row_ror:8 row_mask:0xf bank_mask:0xf
	v_add_f32_dpp v123, v123, v123 row_ror:8 row_mask:0xf bank_mask:0xf
	v_add_f32_dpp v114, v114, v114 row_ror:8 row_mask:0xf bank_mask:0xf
	v_add_f32_dpp v115, v115, v115 row_ror:8 row_mask:0xf bank_mask:0xf
	v_lshl_add_u64 v[146:147], v[144:145], 0, v[146:147]
	v_and_b32_e32 v8, 48, v216
	v_lshlrev_b32_e32 v8, 4, v8
	v_mov_b32_e32 v9, 0
	v_lshl_add_u64 v[146:147], v[146:147], 0, v[8:9]
	v_cvt_pk_f16_f32 v0, v110, v111
	v_cvt_pk_f16_f32 v1, v112, v113
	v_cvt_pk_f16_f32 v2, v118, v119
	v_cvt_pk_f16_f32 v3, v116, v117
	v_cvt_pk_f16_f32 v4, v120, v121
	v_cvt_pk_f16_f32 v5, v108, v109
	v_cvt_pk_f16_f32 v6, v122, v123
	v_cvt_pk_f16_f32 v7, v114, v115
	s_mov_b64 s[50:51], exec
	s_mov_b32 exec_lo, 0xff00ff
	s_mov_b32 exec_hi, 0xff00ff
	global_store_dwordx4 v[146:147], v[0:3], off
	global_store_dwordx4 v[146:147], v[4:7], off offset:16
	s_nop 1
	s_branch .LBB0_843
